# GEMM K-loops: s_setprio raise moved before the phase-opening barrier and the drop moved after the phase-closing barrier (two fewer instructions between barrier release and first MFMA)
# speedup vs baseline: 1.0255x; 1.0058x over previous
.LBB0_221:
	ds_read_b128 v[148:151], v161
	ds_read_b128 v[164:167], v161 offset:1024
	ds_read_b128 v[168:171], v161 offset:2048
	ds_read_b128 v[174:177], v161 offset:3072
	ds_read_b128 v[178:181], v162
	ds_read_b128 v[182:185], v162 offset:1024
	ds_read_b128 v[186:189], v162 offset:2048
	ds_read_b128 v[190:193], v162 offset:3072
	s_add_u32 s40, s38, 0xfff80080
	s_addc_u32 s41, s39, -1
	s_cmp_eq_u32 s72, 28
	s_cselect_b32 s43, s5, s41
	s_cselect_b32 s42, s29, s40
	s_cselect_b32 s41, s25, s71
	s_cselect_b32 s40, s69, s70
	v_lshl_add_u64 v[226:227], s[38:39], 0, v[140:141]
	s_add_i32 m0, s27, 0xc000
	ds_read_b128 v[194:197], v163
	ds_read_b128 v[198:201], v163 offset:1024
	ds_read_b128 v[202:205], v163 offset:2048
	ds_read_b128 v[206:209], v163 offset:3072
	ds_read_b128 v[210:213], v163 offset:4096
	ds_read_b128 v[214:217], v163 offset:5120
	ds_read_b128 v[218:221], v163 offset:6144
	ds_read_b128 v[222:225], v163 offset:7168
	global_load_lds_dwordx4 v[226:227], off
	v_lshl_add_u64 v[226:227], s[38:39], 0, v[142:143]
	s_add_i32 m0, s27, 0xe000
	s_nop 0
	global_load_lds_dwordx4 v[226:227], off
	s_waitcnt vmcnt(8)
	s_waitcnt lgkmcnt(0)
	s_setprio 1
	s_barrier
	s_waitcnt lgkmcnt(0)
	v_mfma_f32_16x16x32_bf16 v[124:127], v[148:151], v[194:197], v[124:127]
	v_mfma_f32_16x16x32_bf16 v[120:123], v[168:171], v[194:197], v[120:123]
	v_mfma_f32_16x16x32_bf16 v[108:111], v[148:151], v[202:205], v[108:111]
	v_mfma_f32_16x16x32_bf16 v[104:107], v[168:171], v[202:205], v[104:107]
	v_mfma_f32_16x16x32_bf16 v[92:95], v[148:151], v[210:213], v[92:95]
	v_mfma_f32_16x16x32_bf16 v[88:91], v[168:171], v[210:213], v[88:91]
	v_mfma_f32_16x16x32_bf16 v[76:79], v[148:151], v[218:221], v[76:79]
	v_mfma_f32_16x16x32_bf16 v[72:75], v[168:171], v[218:221], v[72:75]
	v_mfma_f32_16x16x32_bf16 v[124:127], v[164:167], v[198:201], v[124:127]
	v_mfma_f32_16x16x32_bf16 v[120:123], v[174:177], v[198:201], v[120:123]
	v_mfma_f32_16x16x32_bf16 v[108:111], v[164:167], v[206:209], v[108:111]
	v_mfma_f32_16x16x32_bf16 v[104:107], v[174:177], v[206:209], v[104:107]
	v_mfma_f32_16x16x32_bf16 v[92:95], v[164:167], v[214:217], v[92:95]
	v_mfma_f32_16x16x32_bf16 v[88:91], v[174:177], v[214:217], v[88:91]
	v_mfma_f32_16x16x32_bf16 v[76:79], v[164:167], v[222:225], v[76:79]
	v_mfma_f32_16x16x32_bf16 v[72:75], v[174:177], v[222:225], v[72:75]
	s_setprio 0
	s_setprio 1
	v_mfma_f32_16x16x32_bf16 v[116:119], v[178:181], v[194:197], v[116:119]
	v_mfma_f32_16x16x32_bf16 v[112:115], v[186:189], v[194:197], v[112:115]
	v_mfma_f32_16x16x32_bf16 v[100:103], v[178:181], v[202:205], v[100:103]
	v_mfma_f32_16x16x32_bf16 v[96:99], v[186:189], v[202:205], v[96:99]
	v_mfma_f32_16x16x32_bf16 v[84:87], v[178:181], v[210:213], v[84:87]
	v_mfma_f32_16x16x32_bf16 v[80:83], v[186:189], v[210:213], v[80:83]
	v_mfma_f32_16x16x32_bf16 v[68:71], v[178:181], v[218:221], v[68:71]
	v_mfma_f32_16x16x32_bf16 v[64:67], v[186:189], v[218:221], v[64:67]
	v_mfma_f32_16x16x32_bf16 v[116:119], v[182:185], v[198:201], v[116:119]
	v_mfma_f32_16x16x32_bf16 v[112:115], v[190:193], v[198:201], v[112:115]
	v_mfma_f32_16x16x32_bf16 v[100:103], v[182:185], v[206:209], v[100:103]
	v_mfma_f32_16x16x32_bf16 v[96:99], v[190:193], v[206:209], v[96:99]
	v_mfma_f32_16x16x32_bf16 v[84:87], v[182:185], v[214:217], v[84:87]
	v_mfma_f32_16x16x32_bf16 v[80:83], v[190:193], v[214:217], v[80:83]
	v_mfma_f32_16x16x32_bf16 v[68:71], v[182:185], v[222:225], v[68:71]
	v_mfma_f32_16x16x32_bf16 v[64:67], v[190:193], v[222:225], v[64:67]
	s_barrier
	s_setprio 0
	s_add_i32 s73, s66, s56
	v_lshl_add_u64 v[226:227], s[40:41], 0, v[134:135]
	s_mov_b32 m0, s73
	ds_read_b128 v[194:197], v163 offset:16384
	ds_read_b128 v[198:201], v163 offset:17408
	ds_read_b128 v[202:205], v163 offset:18432
	ds_read_b128 v[206:209], v163 offset:19456
	ds_read_b128 v[210:213], v163 offset:20480
	ds_read_b128 v[214:217], v163 offset:21504
	ds_read_b128 v[218:221], v163 offset:22528
	ds_read_b128 v[222:225], v163 offset:23552
	global_load_lds_dwordx4 v[226:227], off
	s_add_i32 m0, s73, 0x2000
	s_add_u32 s78, s40, 0x80000
	v_lshl_add_u64 v[228:229], s[40:41], 0, v[136:137]
	s_addc_u32 s79, s41, 0
	s_add_i32 s73, s67, s56
	global_load_lds_dwordx4 v[228:229], off
	v_lshl_add_u64 v[230:231], s[78:79], 0, v[134:135]
	s_mov_b32 m0, s73
	v_lshl_add_u64 v[232:233], s[42:43], 0, v[132:133]
	global_load_lds_dwordx4 v[230:231], off
	v_lshl_add_u64 v[230:231], s[78:79], 0, v[136:137]
	s_add_i32 m0, s73, 0x2000
	s_nop 0
	global_load_lds_dwordx4 v[230:231], off
	v_lshl_add_u64 v[230:231], s[42:43], 0, v[130:131]
	s_mov_b32 m0, s27
	s_nop 0
	global_load_lds_dwordx4 v[230:231], off
	s_mov_b32 m0, s57
	s_nop 0
	global_load_lds_dwordx4 v[232:233], off
	s_waitcnt vmcnt(8)
	s_waitcnt lgkmcnt(0)
	s_setprio 1
	s_barrier
	s_waitcnt lgkmcnt(0)
	v_mfma_f32_16x16x32_bf16 v[60:63], v[148:151], v[194:197], v[60:63]
	v_mfma_f32_16x16x32_bf16 v[56:59], v[168:171], v[194:197], v[56:59]
	v_mfma_f32_16x16x32_bf16 v[44:47], v[148:151], v[202:205], v[44:47]
	v_mfma_f32_16x16x32_bf16 v[40:43], v[168:171], v[202:205], v[40:43]
	v_mfma_f32_16x16x32_bf16 v[28:31], v[148:151], v[210:213], v[28:31]
	v_mfma_f32_16x16x32_bf16 v[24:27], v[168:171], v[210:213], v[24:27]
	v_mfma_f32_16x16x32_bf16 v[12:15], v[148:151], v[218:221], v[12:15]
	v_mfma_f32_16x16x32_bf16 v[8:11], v[168:171], v[218:221], v[8:11]
	v_mfma_f32_16x16x32_bf16 v[60:63], v[164:167], v[198:201], v[60:63]
	v_mfma_f32_16x16x32_bf16 v[56:59], v[174:177], v[198:201], v[56:59]
	v_mfma_f32_16x16x32_bf16 v[44:47], v[164:167], v[206:209], v[44:47]
	v_mfma_f32_16x16x32_bf16 v[40:43], v[174:177], v[206:209], v[40:43]
	v_mfma_f32_16x16x32_bf16 v[28:31], v[164:167], v[214:217], v[28:31]
	v_mfma_f32_16x16x32_bf16 v[24:27], v[174:177], v[214:217], v[24:27]
	v_mfma_f32_16x16x32_bf16 v[12:15], v[164:167], v[222:225], v[12:15]
	v_mfma_f32_16x16x32_bf16 v[8:11], v[174:177], v[222:225], v[8:11]
	s_setprio 0
	s_setprio 1
	v_mfma_f32_16x16x32_bf16 v[52:55], v[178:181], v[194:197], v[52:55]
	v_mfma_f32_16x16x32_bf16 v[48:51], v[186:189], v[194:197], v[48:51]
	v_mfma_f32_16x16x32_bf16 v[36:39], v[178:181], v[202:205], v[36:39]
	v_mfma_f32_16x16x32_bf16 v[32:35], v[186:189], v[202:205], v[32:35]
	v_mfma_f32_16x16x32_bf16 v[20:23], v[178:181], v[210:213], v[20:23]
	v_mfma_f32_16x16x32_bf16 v[16:19], v[186:189], v[210:213], v[16:19]
	v_mfma_f32_16x16x32_bf16 v[4:7], v[178:181], v[218:221], v[4:7]
	v_mfma_f32_16x16x32_bf16 v[0:3], v[186:189], v[218:221], v[0:3]
	v_mfma_f32_16x16x32_bf16 v[52:55], v[182:185], v[198:201], v[52:55]
	v_mfma_f32_16x16x32_bf16 v[48:51], v[190:193], v[198:201], v[48:51]
	v_mfma_f32_16x16x32_bf16 v[36:39], v[182:185], v[206:209], v[36:39]
	v_mfma_f32_16x16x32_bf16 v[32:35], v[190:193], v[206:209], v[32:35]
	v_mfma_f32_16x16x32_bf16 v[20:23], v[182:185], v[214:217], v[20:23]
	v_mfma_f32_16x16x32_bf16 v[16:19], v[190:193], v[214:217], v[16:19]
	v_mfma_f32_16x16x32_bf16 v[4:7], v[182:185], v[222:225], v[4:7]
	v_mfma_f32_16x16x32_bf16 v[0:3], v[190:193], v[222:225], v[0:3]
	s_barrier
	s_setprio 0
	s_add_i32 s73, 0, 0x18000
	v_add_u32_e32 v173, s73, v159
	s_add_i32 s78, 0, 0x1c000
	ds_read_b128 v[148:151], v173
	ds_read_b128 v[164:167], v173 offset:1024
	ds_read_b128 v[168:171], v173 offset:2048
	ds_read_b128 v[174:177], v173 offset:3072
	v_add_u32_e32 v173, s78, v159
	ds_read_b128 v[178:181], v173
	ds_read_b128 v[182:185], v173 offset:1024
	ds_read_b128 v[186:189], v173 offset:2048
	ds_read_b128 v[190:193], v173 offset:3072
	s_add_u32 s42, s42, 0x80000
	s_addc_u32 s43, s43, 0
	s_mov_b32 m0, s58
	v_lshl_add_u64 v[234:235], s[42:43], 0, v[130:131]
	ds_read_b128 v[194:197], v163 offset:32768
	ds_read_b128 v[198:201], v163 offset:33792
	ds_read_b128 v[202:205], v163 offset:34816
	ds_read_b128 v[206:209], v163 offset:35840
	ds_read_b128 v[210:213], v163 offset:36864
	ds_read_b128 v[214:217], v163 offset:37888
	ds_read_b128 v[218:221], v163 offset:38912
	ds_read_b128 v[222:225], v163 offset:39936
	global_load_lds_dwordx4 v[234:235], off
	v_lshl_add_u64 v[234:235], s[42:43], 0, v[132:133]
	s_mov_b32 m0, s59
	s_nop 0
	global_load_lds_dwordx4 v[234:235], off
	s_waitcnt vmcnt(8)
	s_waitcnt lgkmcnt(0)
	s_setprio 1
	s_barrier
	s_waitcnt lgkmcnt(0)
	v_mfma_f32_16x16x32_bf16 v[124:127], v[148:151], v[194:197], v[124:127]
	v_mfma_f32_16x16x32_bf16 v[120:123], v[168:171], v[194:197], v[120:123]
	v_mfma_f32_16x16x32_bf16 v[108:111], v[148:151], v[202:205], v[108:111]
	v_mfma_f32_16x16x32_bf16 v[104:107], v[168:171], v[202:205], v[104:107]
	v_mfma_f32_16x16x32_bf16 v[92:95], v[148:151], v[210:213], v[92:95]
	v_mfma_f32_16x16x32_bf16 v[88:91], v[168:171], v[210:213], v[88:91]
	v_mfma_f32_16x16x32_bf16 v[76:79], v[148:151], v[218:221], v[76:79]
	v_mfma_f32_16x16x32_bf16 v[72:75], v[168:171], v[218:221], v[72:75]
	v_mfma_f32_16x16x32_bf16 v[124:127], v[164:167], v[198:201], v[124:127]
	v_mfma_f32_16x16x32_bf16 v[120:123], v[174:177], v[198:201], v[120:123]
	v_mfma_f32_16x16x32_bf16 v[108:111], v[164:167], v[206:209], v[108:111]
	v_mfma_f32_16x16x32_bf16 v[104:107], v[174:177], v[206:209], v[104:107]
	v_mfma_f32_16x16x32_bf16 v[92:95], v[164:167], v[214:217], v[92:95]
	v_mfma_f32_16x16x32_bf16 v[88:91], v[174:177], v[214:217], v[88:91]
	v_mfma_f32_16x16x32_bf16 v[76:79], v[164:167], v[222:225], v[76:79]
	v_mfma_f32_16x16x32_bf16 v[72:75], v[174:177], v[222:225], v[72:75]
	s_setprio 0
	s_setprio 1
	v_mfma_f32_16x16x32_bf16 v[116:119], v[178:181], v[194:197], v[116:119]
	v_mfma_f32_16x16x32_bf16 v[112:115], v[186:189], v[194:197], v[112:115]
	v_mfma_f32_16x16x32_bf16 v[100:103], v[178:181], v[202:205], v[100:103]
	v_mfma_f32_16x16x32_bf16 v[96:99], v[186:189], v[202:205], v[96:99]
	v_mfma_f32_16x16x32_bf16 v[84:87], v[178:181], v[210:213], v[84:87]
	v_mfma_f32_16x16x32_bf16 v[80:83], v[186:189], v[210:213], v[80:83]
	v_mfma_f32_16x16x32_bf16 v[68:71], v[178:181], v[218:221], v[68:71]
	v_mfma_f32_16x16x32_bf16 v[64:67], v[186:189], v[218:221], v[64:67]
	v_mfma_f32_16x16x32_bf16 v[116:119], v[182:185], v[198:201], v[116:119]
	v_mfma_f32_16x16x32_bf16 v[112:115], v[190:193], v[198:201], v[112:115]
	v_mfma_f32_16x16x32_bf16 v[100:103], v[182:185], v[206:209], v[100:103]
	v_mfma_f32_16x16x32_bf16 v[96:99], v[190:193], v[206:209], v[96:99]
	v_mfma_f32_16x16x32_bf16 v[84:87], v[182:185], v[214:217], v[84:87]
	v_mfma_f32_16x16x32_bf16 v[80:83], v[190:193], v[214:217], v[80:83]
	v_mfma_f32_16x16x32_bf16 v[68:71], v[182:185], v[222:225], v[68:71]
	v_mfma_f32_16x16x32_bf16 v[64:67], v[190:193], v[222:225], v[64:67]
	s_barrier
	s_setprio 0
	s_add_i32 s42, s73, s56
	v_lshl_add_u64 v[226:227], v[226:227], 0, s[10:11]
	s_mov_b32 m0, s42
	ds_read_b128 v[194:197], v163 offset:49152
	ds_read_b128 v[198:201], v163 offset:50176
	ds_read_b128 v[202:205], v163 offset:51200
	ds_read_b128 v[206:209], v163 offset:52224
	ds_read_b128 v[210:213], v163 offset:53248
	ds_read_b128 v[214:217], v163 offset:54272
	ds_read_b128 v[218:221], v163 offset:55296
	ds_read_b128 v[222:225], v163 offset:56320
	global_load_lds_dwordx4 v[226:227], off
	s_add_i32 m0, s42, 0x2000
	s_add_u32 s40, s40, 0x80080
	v_lshl_add_u64 v[226:227], v[228:229], 0, s[10:11]
	s_addc_u32 s41, s41, 0
	s_add_i32 s42, s78, s56
	global_load_lds_dwordx4 v[226:227], off
	v_lshl_add_u64 v[226:227], s[40:41], 0, v[134:135]
	s_mov_b32 m0, s42
	s_nop 0
	global_load_lds_dwordx4 v[226:227], off
	v_lshl_add_u64 v[226:227], s[40:41], 0, v[136:137]
	s_add_i32 m0, s42, 0x2000
	s_nop 0
	global_load_lds_dwordx4 v[226:227], off
	v_lshl_add_u64 v[226:227], v[230:231], 0, s[10:11]
	s_mov_b32 m0, s61
	s_nop 0
	global_load_lds_dwordx4 v[226:227], off
	v_lshl_add_u64 v[226:227], v[232:233], 0, s[10:11]
	s_mov_b32 m0, s62
	s_nop 0
	global_load_lds_dwordx4 v[226:227], off
	s_waitcnt vmcnt(8)
	s_waitcnt lgkmcnt(0)
	s_setprio 1
	s_barrier
	s_waitcnt lgkmcnt(0)
	v_mfma_f32_16x16x32_bf16 v[60:63], v[148:151], v[194:197], v[60:63]
	v_mfma_f32_16x16x32_bf16 v[56:59], v[168:171], v[194:197], v[56:59]
	v_mfma_f32_16x16x32_bf16 v[44:47], v[148:151], v[202:205], v[44:47]
	v_mfma_f32_16x16x32_bf16 v[40:43], v[168:171], v[202:205], v[40:43]
	v_mfma_f32_16x16x32_bf16 v[28:31], v[148:151], v[210:213], v[28:31]
	v_mfma_f32_16x16x32_bf16 v[24:27], v[168:171], v[210:213], v[24:27]
	v_mfma_f32_16x16x32_bf16 v[12:15], v[148:151], v[218:221], v[12:15]
	v_mfma_f32_16x16x32_bf16 v[8:11], v[168:171], v[218:221], v[8:11]
	v_mfma_f32_16x16x32_bf16 v[60:63], v[164:167], v[198:201], v[60:63]
	v_mfma_f32_16x16x32_bf16 v[56:59], v[174:177], v[198:201], v[56:59]
	v_mfma_f32_16x16x32_bf16 v[44:47], v[164:167], v[206:209], v[44:47]
	v_mfma_f32_16x16x32_bf16 v[40:43], v[174:177], v[206:209], v[40:43]
	v_mfma_f32_16x16x32_bf16 v[28:31], v[164:167], v[214:217], v[28:31]
	v_mfma_f32_16x16x32_bf16 v[24:27], v[174:177], v[214:217], v[24:27]
	v_mfma_f32_16x16x32_bf16 v[12:15], v[164:167], v[222:225], v[12:15]
	v_mfma_f32_16x16x32_bf16 v[8:11], v[174:177], v[222:225], v[8:11]
	s_setprio 0
	s_setprio 1
	v_mfma_f32_16x16x32_bf16 v[52:55], v[178:181], v[194:197], v[52:55]
	v_mfma_f32_16x16x32_bf16 v[48:51], v[186:189], v[194:197], v[48:51]
	v_mfma_f32_16x16x32_bf16 v[36:39], v[178:181], v[202:205], v[36:39]
	v_mfma_f32_16x16x32_bf16 v[32:35], v[186:189], v[202:205], v[32:35]
	v_mfma_f32_16x16x32_bf16 v[20:23], v[178:181], v[210:213], v[20:23]
	v_mfma_f32_16x16x32_bf16 v[16:19], v[186:189], v[210:213], v[16:19]
	v_mfma_f32_16x16x32_bf16 v[4:7], v[178:181], v[218:221], v[4:7]
	v_mfma_f32_16x16x32_bf16 v[0:3], v[186:189], v[218:221], v[0:3]
	v_mfma_f32_16x16x32_bf16 v[52:55], v[182:185], v[198:201], v[52:55]
	v_mfma_f32_16x16x32_bf16 v[48:51], v[190:193], v[198:201], v[48:51]
	v_mfma_f32_16x16x32_bf16 v[36:39], v[182:185], v[206:209], v[36:39]
	v_mfma_f32_16x16x32_bf16 v[32:35], v[190:193], v[206:209], v[32:35]
	v_mfma_f32_16x16x32_bf16 v[20:23], v[182:185], v[214:217], v[20:23]
	v_mfma_f32_16x16x32_bf16 v[16:19], v[190:193], v[214:217], v[16:19]
	v_mfma_f32_16x16x32_bf16 v[4:7], v[182:185], v[222:225], v[4:7]
	v_mfma_f32_16x16x32_bf16 v[0:3], v[190:193], v[222:225], v[0:3]
	s_barrier
	s_setprio 0
	s_add_i32 s72, s72, 2
	s_add_u32 s38, s38, 0x100
	s_addc_u32 s39, s39, 0
	s_add_u32 s70, s70, 0x100
	s_addc_u32 s71, s71, 0
	s_cmp_gt_u32 s72, 29
	s_cbranch_scc0 .LBB0_221
	s_and_b64 vcc, exec, s[12:13]
	s_cbranch_vccz .LBB0_224
	s_barrier

.LBB0_261:
	ds_read_b128 v[146:149], v129
	ds_read_b128 v[150:153], v129 offset:1024
	ds_read_b128 v[154:157], v129 offset:2048
	ds_read_b128 v[158:161], v129 offset:3072
	ds_read_b128 v[162:165], v143
	ds_read_b128 v[166:169], v143 offset:1024
	ds_read_b128 v[174:177], v143 offset:2048
	ds_read_b128 v[178:181], v143 offset:3072
	s_add_u32 s30, s28, 0xfff80080
	s_addc_u32 s31, s29, -1
	s_cmp_eq_u32 s68, 28
	s_cselect_b32 s35, s15, s31
	s_cselect_b32 s34, s64, s30
	s_cselect_b32 s31, s13, s67
	s_cselect_b32 s30, s65, s66
	v_lshl_add_u64 v[170:171], s[28:29], 0, v[136:137]
	s_add_i32 m0, s53, 0xc000
	ds_read_b128 v[182:185], v144
	ds_read_b128 v[186:189], v144 offset:1024
	ds_read_b128 v[190:193], v144 offset:2048
	ds_read_b128 v[194:197], v144 offset:3072
	ds_read_b128 v[198:201], v144 offset:4096
	ds_read_b128 v[202:205], v144 offset:5120
	ds_read_b128 v[206:209], v144 offset:6144
	ds_read_b128 v[210:213], v144 offset:7168
	global_load_lds_dwordx4 v[170:171], off
	v_lshl_add_u64 v[170:171], s[28:29], 0, v[138:139]
	s_add_i32 m0, s53, 0xe000
	s_nop 0
	global_load_lds_dwordx4 v[170:171], off
	s_waitcnt vmcnt(8)
	s_waitcnt lgkmcnt(0)
	s_setprio 1
	s_barrier
	s_waitcnt lgkmcnt(0)
	v_mfma_f32_16x16x32_bf16 v[124:127], v[146:149], v[182:185], v[124:127]
	v_mfma_f32_16x16x32_bf16 v[120:123], v[154:157], v[182:185], v[120:123]
	v_mfma_f32_16x16x32_bf16 v[116:119], v[146:149], v[190:193], v[116:119]
	v_mfma_f32_16x16x32_bf16 v[112:115], v[154:157], v[190:193], v[112:115]
	v_mfma_f32_16x16x32_bf16 v[104:107], v[146:149], v[198:201], v[104:107]
	v_mfma_f32_16x16x32_bf16 v[96:99], v[154:157], v[198:201], v[96:99]
	v_mfma_f32_16x16x32_bf16 v[88:91], v[146:149], v[206:209], v[88:91]
	v_mfma_f32_16x16x32_bf16 v[80:83], v[154:157], v[206:209], v[80:83]
	v_mfma_f32_16x16x32_bf16 v[124:127], v[150:153], v[186:189], v[124:127]
	v_mfma_f32_16x16x32_bf16 v[120:123], v[158:161], v[186:189], v[120:123]
	v_mfma_f32_16x16x32_bf16 v[116:119], v[150:153], v[194:197], v[116:119]
	v_mfma_f32_16x16x32_bf16 v[112:115], v[158:161], v[194:197], v[112:115]
	v_mfma_f32_16x16x32_bf16 v[104:107], v[150:153], v[202:205], v[104:107]
	v_mfma_f32_16x16x32_bf16 v[96:99], v[158:161], v[202:205], v[96:99]
	v_mfma_f32_16x16x32_bf16 v[88:91], v[150:153], v[210:213], v[88:91]
	v_mfma_f32_16x16x32_bf16 v[80:83], v[158:161], v[210:213], v[80:83]
	s_setprio 0
	s_setprio 1
	v_mfma_f32_16x16x32_bf16 v[108:111], v[162:165], v[182:185], v[108:111]
	v_mfma_f32_16x16x32_bf16 v[100:103], v[174:177], v[182:185], v[100:103]
	v_mfma_f32_16x16x32_bf16 v[92:95], v[162:165], v[190:193], v[92:95]
	v_mfma_f32_16x16x32_bf16 v[84:87], v[174:177], v[190:193], v[84:87]
	v_mfma_f32_16x16x32_bf16 v[76:79], v[162:165], v[198:201], v[76:79]
	v_mfma_f32_16x16x32_bf16 v[72:75], v[174:177], v[198:201], v[72:75]
	v_mfma_f32_16x16x32_bf16 v[68:71], v[162:165], v[206:209], v[68:71]
	v_mfma_f32_16x16x32_bf16 v[64:67], v[174:177], v[206:209], v[64:67]
	v_mfma_f32_16x16x32_bf16 v[108:111], v[166:169], v[186:189], v[108:111]
	v_mfma_f32_16x16x32_bf16 v[100:103], v[178:181], v[186:189], v[100:103]
	v_mfma_f32_16x16x32_bf16 v[92:95], v[166:169], v[194:197], v[92:95]
	v_mfma_f32_16x16x32_bf16 v[84:87], v[178:181], v[194:197], v[84:87]
	v_mfma_f32_16x16x32_bf16 v[76:79], v[166:169], v[202:205], v[76:79]
	v_mfma_f32_16x16x32_bf16 v[72:75], v[178:181], v[202:205], v[72:75]
	v_mfma_f32_16x16x32_bf16 v[68:71], v[166:169], v[210:213], v[68:71]
	v_mfma_f32_16x16x32_bf16 v[64:67], v[178:181], v[210:213], v[64:67]
	s_barrier
	s_setprio 0
	s_add_i32 s69, s62, s52
	v_lshl_add_u64 v[170:171], s[30:31], 0, v[130:131]
	s_mov_b32 m0, s69
	ds_read_b128 v[182:185], v144 offset:16384
	ds_read_b128 v[186:189], v144 offset:17408
	ds_read_b128 v[190:193], v144 offset:18432
	ds_read_b128 v[194:197], v144 offset:19456
	ds_read_b128 v[198:201], v144 offset:20480
	ds_read_b128 v[202:205], v144 offset:21504
	ds_read_b128 v[206:209], v144 offset:22528
	ds_read_b128 v[210:213], v144 offset:23552
	global_load_lds_dwordx4 v[170:171], off
	s_add_i32 m0, s69, 0x2000
	s_add_u32 s70, s30, 0x80000
	v_lshl_add_u64 v[214:215], s[30:31], 0, v[132:133]
	s_addc_u32 s71, s31, 0
	s_add_i32 s69, s63, s52
	global_load_lds_dwordx4 v[214:215], off
	v_lshl_add_u64 v[216:217], s[70:71], 0, v[130:131]
	s_mov_b32 m0, s69
	v_lshl_add_u64 v[218:219], s[34:35], 0, v[132:133]
	global_load_lds_dwordx4 v[216:217], off
	v_lshl_add_u64 v[216:217], s[70:71], 0, v[132:133]
	s_add_i32 m0, s69, 0x2000
	s_nop 0
	global_load_lds_dwordx4 v[216:217], off
	v_lshl_add_u64 v[216:217], s[34:35], 0, v[130:131]
	s_mov_b32 m0, s53
	s_nop 0
	global_load_lds_dwordx4 v[216:217], off
	s_mov_b32 m0, s54
	s_nop 0
	global_load_lds_dwordx4 v[218:219], off
	s_waitcnt vmcnt(8)
	s_waitcnt lgkmcnt(0)
	s_setprio 1
	s_barrier
	s_waitcnt lgkmcnt(0)
	v_mfma_f32_16x16x32_bf16 v[60:63], v[146:149], v[182:185], v[60:63]
	v_mfma_f32_16x16x32_bf16 v[56:59], v[154:157], v[182:185], v[56:59]
	v_mfma_f32_16x16x32_bf16 v[52:55], v[146:149], v[190:193], v[52:55]
	v_mfma_f32_16x16x32_bf16 v[48:51], v[154:157], v[190:193], v[48:51]
	v_mfma_f32_16x16x32_bf16 v[40:43], v[146:149], v[198:201], v[40:43]
	v_mfma_f32_16x16x32_bf16 v[32:35], v[154:157], v[198:201], v[32:35]
	v_mfma_f32_16x16x32_bf16 v[24:27], v[146:149], v[206:209], v[24:27]
	v_mfma_f32_16x16x32_bf16 v[16:19], v[154:157], v[206:209], v[16:19]
	v_mfma_f32_16x16x32_bf16 v[60:63], v[150:153], v[186:189], v[60:63]
	v_mfma_f32_16x16x32_bf16 v[56:59], v[158:161], v[186:189], v[56:59]
	v_mfma_f32_16x16x32_bf16 v[52:55], v[150:153], v[194:197], v[52:55]
	v_mfma_f32_16x16x32_bf16 v[48:51], v[158:161], v[194:197], v[48:51]
	v_mfma_f32_16x16x32_bf16 v[40:43], v[150:153], v[202:205], v[40:43]
	v_mfma_f32_16x16x32_bf16 v[32:35], v[158:161], v[202:205], v[32:35]
	v_mfma_f32_16x16x32_bf16 v[24:27], v[150:153], v[210:213], v[24:27]
	v_mfma_f32_16x16x32_bf16 v[16:19], v[158:161], v[210:213], v[16:19]
	s_setprio 0
	s_setprio 1
	v_mfma_f32_16x16x32_bf16 v[44:47], v[162:165], v[182:185], v[44:47]
	v_mfma_f32_16x16x32_bf16 v[36:39], v[174:177], v[182:185], v[36:39]
	v_mfma_f32_16x16x32_bf16 v[28:31], v[162:165], v[190:193], v[28:31]
	v_mfma_f32_16x16x32_bf16 v[20:23], v[174:177], v[190:193], v[20:23]
	v_mfma_f32_16x16x32_bf16 v[12:15], v[162:165], v[198:201], v[12:15]
	v_mfma_f32_16x16x32_bf16 v[8:11], v[174:177], v[198:201], v[8:11]
	v_mfma_f32_16x16x32_bf16 v[4:7], v[162:165], v[206:209], v[4:7]
	v_mfma_f32_16x16x32_bf16 v[0:3], v[174:177], v[206:209], v[0:3]
	v_mfma_f32_16x16x32_bf16 v[44:47], v[166:169], v[186:189], v[44:47]
	v_mfma_f32_16x16x32_bf16 v[36:39], v[178:181], v[186:189], v[36:39]
	v_mfma_f32_16x16x32_bf16 v[28:31], v[166:169], v[194:197], v[28:31]
	v_mfma_f32_16x16x32_bf16 v[20:23], v[178:181], v[194:197], v[20:23]
	v_mfma_f32_16x16x32_bf16 v[12:15], v[166:169], v[202:205], v[12:15]
	v_mfma_f32_16x16x32_bf16 v[8:11], v[178:181], v[202:205], v[8:11]
	v_mfma_f32_16x16x32_bf16 v[4:7], v[166:169], v[210:213], v[4:7]
	v_mfma_f32_16x16x32_bf16 v[0:3], v[178:181], v[210:213], v[0:3]
	s_barrier
	s_setprio 0
	s_add_i32 s69, 0, 0x18000
	v_add_u32_e32 v134, s69, v141
	s_add_i32 s70, 0, 0x1c000
	ds_read_b128 v[146:149], v134
	ds_read_b128 v[150:153], v134 offset:1024
	ds_read_b128 v[154:157], v134 offset:2048
	ds_read_b128 v[158:161], v134 offset:3072
	v_add_u32_e32 v134, s70, v141
	ds_read_b128 v[162:165], v134
	ds_read_b128 v[166:169], v134 offset:1024
	ds_read_b128 v[174:177], v134 offset:2048
	ds_read_b128 v[178:181], v134 offset:3072
	s_add_u32 s34, s34, 0x80000
	s_addc_u32 s35, s35, 0
	s_mov_b32 m0, s55
	v_lshl_add_u64 v[220:221], s[34:35], 0, v[130:131]
	ds_read_b128 v[182:185], v144 offset:32768
	ds_read_b128 v[186:189], v144 offset:33792
	ds_read_b128 v[190:193], v144 offset:34816
	ds_read_b128 v[194:197], v144 offset:35840
	ds_read_b128 v[198:201], v144 offset:36864
	ds_read_b128 v[202:205], v144 offset:37888
	ds_read_b128 v[206:209], v144 offset:38912
	ds_read_b128 v[210:213], v144 offset:39936
	global_load_lds_dwordx4 v[220:221], off
	v_lshl_add_u64 v[220:221], s[34:35], 0, v[132:133]
	s_mov_b32 m0, s56
	s_nop 0
	global_load_lds_dwordx4 v[220:221], off
	s_waitcnt vmcnt(8)
	s_waitcnt lgkmcnt(0)
	s_setprio 1
	s_barrier
	s_waitcnt lgkmcnt(0)
	v_mfma_f32_16x16x32_bf16 v[124:127], v[146:149], v[182:185], v[124:127]
	v_mfma_f32_16x16x32_bf16 v[120:123], v[154:157], v[182:185], v[120:123]
	v_mfma_f32_16x16x32_bf16 v[116:119], v[146:149], v[190:193], v[116:119]
	v_mfma_f32_16x16x32_bf16 v[112:115], v[154:157], v[190:193], v[112:115]
	v_mfma_f32_16x16x32_bf16 v[104:107], v[146:149], v[198:201], v[104:107]
	v_mfma_f32_16x16x32_bf16 v[96:99], v[154:157], v[198:201], v[96:99]
	v_mfma_f32_16x16x32_bf16 v[88:91], v[146:149], v[206:209], v[88:91]
	v_mfma_f32_16x16x32_bf16 v[80:83], v[154:157], v[206:209], v[80:83]
	v_mfma_f32_16x16x32_bf16 v[124:127], v[150:153], v[186:189], v[124:127]
	v_mfma_f32_16x16x32_bf16 v[120:123], v[158:161], v[186:189], v[120:123]
	v_mfma_f32_16x16x32_bf16 v[116:119], v[150:153], v[194:197], v[116:119]
	v_mfma_f32_16x16x32_bf16 v[112:115], v[158:161], v[194:197], v[112:115]
	v_mfma_f32_16x16x32_bf16 v[104:107], v[150:153], v[202:205], v[104:107]
	v_mfma_f32_16x16x32_bf16 v[96:99], v[158:161], v[202:205], v[96:99]
	v_mfma_f32_16x16x32_bf16 v[88:91], v[150:153], v[210:213], v[88:91]
	v_mfma_f32_16x16x32_bf16 v[80:83], v[158:161], v[210:213], v[80:83]
	s_setprio 0
	s_setprio 1
	v_mfma_f32_16x16x32_bf16 v[108:111], v[162:165], v[182:185], v[108:111]
	v_mfma_f32_16x16x32_bf16 v[100:103], v[174:177], v[182:185], v[100:103]
	v_mfma_f32_16x16x32_bf16 v[92:95], v[162:165], v[190:193], v[92:95]
	v_mfma_f32_16x16x32_bf16 v[84:87], v[174:177], v[190:193], v[84:87]
	v_mfma_f32_16x16x32_bf16 v[76:79], v[162:165], v[198:201], v[76:79]
	v_mfma_f32_16x16x32_bf16 v[72:75], v[174:177], v[198:201], v[72:75]
	v_mfma_f32_16x16x32_bf16 v[68:71], v[162:165], v[206:209], v[68:71]
	v_mfma_f32_16x16x32_bf16 v[64:67], v[174:177], v[206:209], v[64:67]
	v_mfma_f32_16x16x32_bf16 v[108:111], v[166:169], v[186:189], v[108:111]
	v_mfma_f32_16x16x32_bf16 v[100:103], v[178:181], v[186:189], v[100:103]
	v_mfma_f32_16x16x32_bf16 v[92:95], v[166:169], v[194:197], v[92:95]
	v_mfma_f32_16x16x32_bf16 v[84:87], v[178:181], v[194:197], v[84:87]
	v_mfma_f32_16x16x32_bf16 v[76:79], v[166:169], v[202:205], v[76:79]
	v_mfma_f32_16x16x32_bf16 v[72:75], v[178:181], v[202:205], v[72:75]
	v_mfma_f32_16x16x32_bf16 v[68:71], v[166:169], v[210:213], v[68:71]
	v_mfma_f32_16x16x32_bf16 v[64:67], v[178:181], v[210:213], v[64:67]
	s_barrier
	s_setprio 0
	s_add_i32 s34, s69, s52
	v_lshl_add_u64 v[170:171], v[170:171], 0, s[4:5]
	s_mov_b32 m0, s34
	ds_read_b128 v[182:185], v144 offset:49152
	ds_read_b128 v[186:189], v144 offset:50176
	ds_read_b128 v[190:193], v144 offset:51200
	ds_read_b128 v[194:197], v144 offset:52224
	ds_read_b128 v[198:201], v144 offset:53248
	ds_read_b128 v[202:205], v144 offset:54272
	ds_read_b128 v[206:209], v144 offset:55296
	ds_read_b128 v[210:213], v144 offset:56320
	global_load_lds_dwordx4 v[170:171], off
	s_add_i32 m0, s34, 0x2000
	s_add_u32 s30, s30, 0x80080
	v_lshl_add_u64 v[170:171], v[214:215], 0, s[4:5]
	s_addc_u32 s31, s31, 0
	s_add_i32 s34, s70, s52
	global_load_lds_dwordx4 v[170:171], off
	v_lshl_add_u64 v[170:171], s[30:31], 0, v[130:131]
	s_mov_b32 m0, s34
	s_nop 0
	global_load_lds_dwordx4 v[170:171], off
	v_lshl_add_u64 v[170:171], s[30:31], 0, v[132:133]
	s_add_i32 m0, s34, 0x2000
	s_nop 0
	global_load_lds_dwordx4 v[170:171], off
	v_lshl_add_u64 v[170:171], v[216:217], 0, s[4:5]
	s_mov_b32 m0, s58
	s_nop 0
	global_load_lds_dwordx4 v[170:171], off
	v_lshl_add_u64 v[170:171], v[218:219], 0, s[4:5]
	s_mov_b32 m0, s59
	s_nop 0
	global_load_lds_dwordx4 v[170:171], off
	s_waitcnt vmcnt(8)
	s_waitcnt lgkmcnt(0)
	s_setprio 1
	s_barrier
	s_waitcnt lgkmcnt(0)
	v_mfma_f32_16x16x32_bf16 v[60:63], v[146:149], v[182:185], v[60:63]
	v_mfma_f32_16x16x32_bf16 v[56:59], v[154:157], v[182:185], v[56:59]
	v_mfma_f32_16x16x32_bf16 v[52:55], v[146:149], v[190:193], v[52:55]
	v_mfma_f32_16x16x32_bf16 v[48:51], v[154:157], v[190:193], v[48:51]
	v_mfma_f32_16x16x32_bf16 v[40:43], v[146:149], v[198:201], v[40:43]
	v_mfma_f32_16x16x32_bf16 v[32:35], v[154:157], v[198:201], v[32:35]
	v_mfma_f32_16x16x32_bf16 v[24:27], v[146:149], v[206:209], v[24:27]
	v_mfma_f32_16x16x32_bf16 v[16:19], v[154:157], v[206:209], v[16:19]
	v_mfma_f32_16x16x32_bf16 v[60:63], v[150:153], v[186:189], v[60:63]
	v_mfma_f32_16x16x32_bf16 v[56:59], v[158:161], v[186:189], v[56:59]
	v_mfma_f32_16x16x32_bf16 v[52:55], v[150:153], v[194:197], v[52:55]
	v_mfma_f32_16x16x32_bf16 v[48:51], v[158:161], v[194:197], v[48:51]
	v_mfma_f32_16x16x32_bf16 v[40:43], v[150:153], v[202:205], v[40:43]
	v_mfma_f32_16x16x32_bf16 v[32:35], v[158:161], v[202:205], v[32:35]
	v_mfma_f32_16x16x32_bf16 v[24:27], v[150:153], v[210:213], v[24:27]
	v_mfma_f32_16x16x32_bf16 v[16:19], v[158:161], v[210:213], v[16:19]
	s_setprio 0
	s_setprio 1
	v_mfma_f32_16x16x32_bf16 v[44:47], v[162:165], v[182:185], v[44:47]
	v_mfma_f32_16x16x32_bf16 v[36:39], v[174:177], v[182:185], v[36:39]
	v_mfma_f32_16x16x32_bf16 v[28:31], v[162:165], v[190:193], v[28:31]
	v_mfma_f32_16x16x32_bf16 v[20:23], v[174:177], v[190:193], v[20:23]
	v_mfma_f32_16x16x32_bf16 v[12:15], v[162:165], v[198:201], v[12:15]
	v_mfma_f32_16x16x32_bf16 v[8:11], v[174:177], v[198:201], v[8:11]
	v_mfma_f32_16x16x32_bf16 v[4:7], v[162:165], v[206:209], v[4:7]
	v_mfma_f32_16x16x32_bf16 v[0:3], v[174:177], v[206:209], v[0:3]
	v_mfma_f32_16x16x32_bf16 v[44:47], v[166:169], v[186:189], v[44:47]
	v_mfma_f32_16x16x32_bf16 v[36:39], v[178:181], v[186:189], v[36:39]
	v_mfma_f32_16x16x32_bf16 v[28:31], v[166:169], v[194:197], v[28:31]
	v_mfma_f32_16x16x32_bf16 v[20:23], v[178:181], v[194:197], v[20:23]
	v_mfma_f32_16x16x32_bf16 v[12:15], v[166:169], v[202:205], v[12:15]
	v_mfma_f32_16x16x32_bf16 v[8:11], v[178:181], v[202:205], v[8:11]
	v_mfma_f32_16x16x32_bf16 v[4:7], v[166:169], v[210:213], v[4:7]
	v_mfma_f32_16x16x32_bf16 v[0:3], v[178:181], v[210:213], v[0:3]
	s_barrier
	s_setprio 0
	s_add_i32 s68, s68, 2
	s_add_u32 s28, s28, 0x100
	s_addc_u32 s29, s29, 0
	s_add_u32 s66, s66, 0x100
	s_addc_u32 s67, s67, 0
	s_cmp_gt_u32 s68, 29
	s_cbranch_scc0 .LBB0_261
	s_and_b64 vcc, exec, s[8:9]
	s_cbranch_vccz .LBB0_264
	s_barrier

.LBB0_623:
	v_add_u32_e32 v1, s53, v152
	ds_read_b128 v[156:159], v1
	ds_read_b128 v[160:163], v1 offset:1024
	ds_read_b128 v[164:167], v1 offset:2048
	ds_read_b128 v[168:171], v1 offset:3072
	v_add_u32_e32 v1, s54, v152
	s_add_u32 s0, s34, s38
	ds_read_b128 v[174:177], v1
	ds_read_b128 v[178:181], v1 offset:1024
	ds_read_b128 v[182:185], v1 offset:2048
	ds_read_b128 v[186:189], v1 offset:3072
	s_addc_u32 s1, s35, s39
	s_add_u32 s0, s0, 0x100
	s_addc_u32 s1, s1, 0
	s_add_u32 s8, s60, s38
	s_addc_u32 s9, s61, s39
	s_cmpk_eq_i32 s38, 0x1700
	s_cselect_b32 s7, s29, s1
	s_cselect_b32 s6, s28, s0
	s_cselect_b32 s1, s31, s9
	s_cselect_b32 s0, s30, s8
	v_lshl_add_u64 v[2:3], v[146:147], 0, s[38:39]
	s_add_i32 m0, s42, 0xc000
	ds_read_b128 v[190:193], v155
	ds_read_b128 v[194:197], v155 offset:1024
	ds_read_b128 v[198:201], v155 offset:2048
	ds_read_b128 v[202:205], v155 offset:3072
	ds_read_b128 v[206:209], v155 offset:4096
	ds_read_b128 v[210:213], v155 offset:5120
	ds_read_b128 v[214:217], v155 offset:6144
	ds_read_b128 v[218:221], v155 offset:7168
	global_load_lds_dwordx4 v[2:3], off
	v_lshl_add_u64 v[2:3], v[148:149], 0, s[38:39]
	s_add_i32 m0, s42, 0xe000
	s_nop 0
	global_load_lds_dwordx4 v[2:3], off
	s_waitcnt vmcnt(8)
	s_waitcnt lgkmcnt(0)
	s_setprio 1
	s_barrier
	s_waitcnt lgkmcnt(0)
	v_mfma_f32_16x16x32_bf16 v[128:131], v[156:159], v[190:193], v[128:131]
	v_mfma_f32_16x16x32_bf16 v[124:127], v[164:167], v[190:193], v[124:127]
	v_mfma_f32_16x16x32_bf16 v[112:115], v[156:159], v[198:201], v[112:115]
	v_mfma_f32_16x16x32_bf16 v[108:111], v[164:167], v[198:201], v[108:111]
	v_mfma_f32_16x16x32_bf16 v[96:99], v[156:159], v[206:209], v[96:99]
	v_mfma_f32_16x16x32_bf16 v[92:95], v[164:167], v[206:209], v[92:95]
	v_mfma_f32_16x16x32_bf16 v[80:83], v[156:159], v[214:217], v[80:83]
	v_mfma_f32_16x16x32_bf16 v[76:79], v[164:167], v[214:217], v[76:79]
	v_mfma_f32_16x16x32_bf16 v[128:131], v[160:163], v[194:197], v[128:131]
	v_mfma_f32_16x16x32_bf16 v[124:127], v[168:171], v[194:197], v[124:127]
	v_mfma_f32_16x16x32_bf16 v[112:115], v[160:163], v[202:205], v[112:115]
	v_mfma_f32_16x16x32_bf16 v[108:111], v[168:171], v[202:205], v[108:111]
	v_mfma_f32_16x16x32_bf16 v[96:99], v[160:163], v[210:213], v[96:99]
	v_mfma_f32_16x16x32_bf16 v[92:95], v[168:171], v[210:213], v[92:95]
	v_mfma_f32_16x16x32_bf16 v[80:83], v[160:163], v[218:221], v[80:83]
	v_mfma_f32_16x16x32_bf16 v[76:79], v[168:171], v[218:221], v[76:79]
	s_setprio 0
	s_setprio 1
	v_mfma_f32_16x16x32_bf16 v[120:123], v[174:177], v[190:193], v[120:123]
	v_mfma_f32_16x16x32_bf16 v[116:119], v[182:185], v[190:193], v[116:119]
	v_mfma_f32_16x16x32_bf16 v[104:107], v[174:177], v[198:201], v[104:107]
	v_mfma_f32_16x16x32_bf16 v[100:103], v[182:185], v[198:201], v[100:103]
	v_mfma_f32_16x16x32_bf16 v[88:91], v[174:177], v[206:209], v[88:91]
	v_mfma_f32_16x16x32_bf16 v[84:87], v[182:185], v[206:209], v[84:87]
	v_mfma_f32_16x16x32_bf16 v[72:75], v[174:177], v[214:217], v[72:75]
	v_mfma_f32_16x16x32_bf16 v[68:71], v[182:185], v[214:217], v[68:71]
	v_mfma_f32_16x16x32_bf16 v[120:123], v[178:181], v[194:197], v[120:123]
	v_mfma_f32_16x16x32_bf16 v[116:119], v[186:189], v[194:197], v[116:119]
	v_mfma_f32_16x16x32_bf16 v[104:107], v[178:181], v[202:205], v[104:107]
	v_mfma_f32_16x16x32_bf16 v[100:103], v[186:189], v[202:205], v[100:103]
	v_mfma_f32_16x16x32_bf16 v[88:91], v[178:181], v[210:213], v[88:91]
	v_mfma_f32_16x16x32_bf16 v[84:87], v[186:189], v[210:213], v[84:87]
	v_mfma_f32_16x16x32_bf16 v[72:75], v[178:181], v[218:221], v[72:75]
	v_mfma_f32_16x16x32_bf16 v[68:71], v[186:189], v[218:221], v[68:71]
	s_barrier
	s_setprio 0
	s_add_i32 s8, s53, s41
	v_lshl_add_u64 v[222:223], s[0:1], 0, v[132:133]
	s_mov_b32 m0, s8
	ds_read_b128 v[190:193], v155 offset:16384
	ds_read_b128 v[194:197], v155 offset:17408
	ds_read_b128 v[198:201], v155 offset:18432
	ds_read_b128 v[202:205], v155 offset:19456
	ds_read_b128 v[206:209], v155 offset:20480
	ds_read_b128 v[210:213], v155 offset:21504
	ds_read_b128 v[214:217], v155 offset:22528
	ds_read_b128 v[218:221], v155 offset:23552
	global_load_lds_dwordx4 v[222:223], off
	s_add_i32 m0, s8, 0x2000
	s_add_u32 s8, s0, 0xc0000
	v_lshl_add_u64 v[224:225], s[0:1], 0, v[134:135]
	s_addc_u32 s9, s1, 0
	s_add_i32 s10, s54, s41
	global_load_lds_dwordx4 v[224:225], off
	v_lshl_add_u64 v[2:3], s[8:9], 0, v[132:133]
	s_mov_b32 m0, s10
	v_lshl_add_u64 v[226:227], s[6:7], 0, v[132:133]
	global_load_lds_dwordx4 v[2:3], off
	v_lshl_add_u64 v[2:3], s[8:9], 0, v[134:135]
	s_add_i32 m0, s10, 0x2000
	v_lshl_add_u64 v[228:229], s[6:7], 0, v[134:135]
	global_load_lds_dwordx4 v[2:3], off
	s_mov_b32 m0, s42
	s_nop 0
	global_load_lds_dwordx4 v[226:227], off
	s_mov_b32 m0, s43
	s_nop 0
	global_load_lds_dwordx4 v[228:229], off
	s_waitcnt vmcnt(8)
	s_waitcnt lgkmcnt(0)
	s_setprio 1
	s_barrier
	s_waitcnt lgkmcnt(0)
	v_mfma_f32_16x16x32_bf16 v[64:67], v[156:159], v[190:193], v[64:67]
	v_mfma_f32_16x16x32_bf16 v[60:63], v[164:167], v[190:193], v[60:63]
	v_mfma_f32_16x16x32_bf16 v[48:51], v[156:159], v[198:201], v[48:51]
	v_mfma_f32_16x16x32_bf16 v[44:47], v[164:167], v[198:201], v[44:47]
	v_mfma_f32_16x16x32_bf16 v[32:35], v[156:159], v[206:209], v[32:35]
	v_mfma_f32_16x16x32_bf16 v[28:31], v[164:167], v[206:209], v[28:31]
	v_mfma_f32_16x16x32_bf16 v[16:19], v[156:159], v[214:217], v[16:19]
	v_mfma_f32_16x16x32_bf16 v[12:15], v[164:167], v[214:217], v[12:15]
	v_mfma_f32_16x16x32_bf16 v[64:67], v[160:163], v[194:197], v[64:67]
	v_mfma_f32_16x16x32_bf16 v[60:63], v[168:171], v[194:197], v[60:63]
	v_mfma_f32_16x16x32_bf16 v[48:51], v[160:163], v[202:205], v[48:51]
	v_mfma_f32_16x16x32_bf16 v[44:47], v[168:171], v[202:205], v[44:47]
	v_mfma_f32_16x16x32_bf16 v[32:35], v[160:163], v[210:213], v[32:35]
	v_mfma_f32_16x16x32_bf16 v[28:31], v[168:171], v[210:213], v[28:31]
	v_mfma_f32_16x16x32_bf16 v[16:19], v[160:163], v[218:221], v[16:19]
	v_mfma_f32_16x16x32_bf16 v[12:15], v[168:171], v[218:221], v[12:15]
	s_setprio 0
	s_setprio 1
	v_mfma_f32_16x16x32_bf16 v[56:59], v[174:177], v[190:193], v[56:59]
	v_mfma_f32_16x16x32_bf16 v[52:55], v[182:185], v[190:193], v[52:55]
	v_mfma_f32_16x16x32_bf16 v[40:43], v[174:177], v[198:201], v[40:43]
	v_mfma_f32_16x16x32_bf16 v[36:39], v[182:185], v[198:201], v[36:39]
	v_mfma_f32_16x16x32_bf16 v[24:27], v[174:177], v[206:209], v[24:27]
	v_mfma_f32_16x16x32_bf16 v[20:23], v[182:185], v[206:209], v[20:23]
	v_mfma_f32_16x16x32_bf16 v[8:11], v[174:177], v[214:217], v[8:11]
	v_mfma_f32_16x16x32_bf16 v[2:5], v[182:185], v[214:217], v[4:7]
	v_mfma_f32_16x16x32_bf16 v[56:59], v[178:181], v[194:197], v[56:59]
	v_mfma_f32_16x16x32_bf16 v[52:55], v[186:189], v[194:197], v[52:55]
	v_mfma_f32_16x16x32_bf16 v[40:43], v[178:181], v[202:205], v[40:43]
	v_mfma_f32_16x16x32_bf16 v[36:39], v[186:189], v[202:205], v[36:39]
	v_mfma_f32_16x16x32_bf16 v[24:27], v[178:181], v[210:213], v[24:27]
	v_mfma_f32_16x16x32_bf16 v[20:23], v[186:189], v[210:213], v[20:23]
	v_mfma_f32_16x16x32_bf16 v[8:11], v[178:181], v[218:221], v[8:11]
	v_mfma_f32_16x16x32_bf16 v[2:5], v[186:189], v[218:221], v[2:5]
	s_barrier
	s_setprio 0
	s_add_i32 s8, 0, 0x18000
	v_add_u32_e32 v1, s8, v152
	s_add_i32 s9, 0, 0x1c000
	ds_read_b128 v[156:159], v1
	ds_read_b128 v[160:163], v1 offset:1024
	ds_read_b128 v[164:167], v1 offset:2048
	ds_read_b128 v[168:171], v1 offset:3072
	v_add_u32_e32 v1, s9, v152
	ds_read_b128 v[174:177], v1
	ds_read_b128 v[178:181], v1 offset:1024
	ds_read_b128 v[182:185], v1 offset:2048
	ds_read_b128 v[186:189], v1 offset:3072
	s_add_u32 s6, s6, 0xc0000
	s_addc_u32 s7, s7, 0
	s_mov_b32 m0, s44
	v_lshl_add_u64 v[6:7], s[6:7], 0, v[132:133]
	ds_read_b128 v[190:193], v155 offset:32768
	ds_read_b128 v[194:197], v155 offset:33792
	ds_read_b128 v[198:201], v155 offset:34816
	ds_read_b128 v[202:205], v155 offset:35840
	ds_read_b128 v[206:209], v155 offset:36864
	ds_read_b128 v[210:213], v155 offset:37888
	ds_read_b128 v[214:217], v155 offset:38912
	ds_read_b128 v[218:221], v155 offset:39936
	global_load_lds_dwordx4 v[6:7], off
	v_lshl_add_u64 v[6:7], s[6:7], 0, v[134:135]
	s_mov_b32 m0, s45
	s_nop 0
	global_load_lds_dwordx4 v[6:7], off
	s_waitcnt vmcnt(8)
	s_waitcnt lgkmcnt(0)
	s_setprio 1
	s_barrier
	s_waitcnt lgkmcnt(0)
	v_mfma_f32_16x16x32_bf16 v[128:131], v[156:159], v[190:193], v[128:131]
	v_mfma_f32_16x16x32_bf16 v[124:127], v[164:167], v[190:193], v[124:127]
	v_mfma_f32_16x16x32_bf16 v[112:115], v[156:159], v[198:201], v[112:115]
	v_mfma_f32_16x16x32_bf16 v[108:111], v[164:167], v[198:201], v[108:111]
	v_mfma_f32_16x16x32_bf16 v[96:99], v[156:159], v[206:209], v[96:99]
	v_mfma_f32_16x16x32_bf16 v[92:95], v[164:167], v[206:209], v[92:95]
	v_mfma_f32_16x16x32_bf16 v[80:83], v[156:159], v[214:217], v[80:83]
	v_mfma_f32_16x16x32_bf16 v[76:79], v[164:167], v[214:217], v[76:79]
	v_mfma_f32_16x16x32_bf16 v[128:131], v[160:163], v[194:197], v[128:131]
	v_mfma_f32_16x16x32_bf16 v[124:127], v[168:171], v[194:197], v[124:127]
	v_mfma_f32_16x16x32_bf16 v[112:115], v[160:163], v[202:205], v[112:115]
	v_mfma_f32_16x16x32_bf16 v[108:111], v[168:171], v[202:205], v[108:111]
	v_mfma_f32_16x16x32_bf16 v[96:99], v[160:163], v[210:213], v[96:99]
	v_mfma_f32_16x16x32_bf16 v[92:95], v[168:171], v[210:213], v[92:95]
	v_mfma_f32_16x16x32_bf16 v[80:83], v[160:163], v[218:221], v[80:83]
	v_mfma_f32_16x16x32_bf16 v[76:79], v[168:171], v[218:221], v[76:79]
	s_setprio 0
	s_setprio 1
	v_mfma_f32_16x16x32_bf16 v[120:123], v[174:177], v[190:193], v[120:123]
	v_mfma_f32_16x16x32_bf16 v[116:119], v[182:185], v[190:193], v[116:119]
	v_mfma_f32_16x16x32_bf16 v[104:107], v[174:177], v[198:201], v[104:107]
	v_mfma_f32_16x16x32_bf16 v[100:103], v[182:185], v[198:201], v[100:103]
	v_mfma_f32_16x16x32_bf16 v[88:91], v[174:177], v[206:209], v[88:91]
	v_mfma_f32_16x16x32_bf16 v[84:87], v[182:185], v[206:209], v[84:87]
	v_mfma_f32_16x16x32_bf16 v[72:75], v[174:177], v[214:217], v[72:75]
	v_mfma_f32_16x16x32_bf16 v[68:71], v[182:185], v[214:217], v[68:71]
	v_mfma_f32_16x16x32_bf16 v[120:123], v[178:181], v[194:197], v[120:123]
	v_mfma_f32_16x16x32_bf16 v[116:119], v[186:189], v[194:197], v[116:119]
	v_mfma_f32_16x16x32_bf16 v[104:107], v[178:181], v[202:205], v[104:107]
	v_mfma_f32_16x16x32_bf16 v[100:103], v[186:189], v[202:205], v[100:103]
	v_mfma_f32_16x16x32_bf16 v[88:91], v[178:181], v[210:213], v[88:91]
	v_mfma_f32_16x16x32_bf16 v[84:87], v[186:189], v[210:213], v[84:87]
	v_mfma_f32_16x16x32_bf16 v[72:75], v[178:181], v[218:221], v[72:75]
	v_mfma_f32_16x16x32_bf16 v[68:71], v[186:189], v[218:221], v[68:71]
	s_barrier
	s_setprio 0
	s_add_i32 s6, s8, s41
	v_lshl_add_u64 v[6:7], v[222:223], 0, s[24:25]
	s_mov_b32 m0, s6
	ds_read_b128 v[190:193], v155 offset:49152
	ds_read_b128 v[194:197], v155 offset:50176
	ds_read_b128 v[198:201], v155 offset:51200
	ds_read_b128 v[202:205], v155 offset:52224
	ds_read_b128 v[206:209], v155 offset:53248
	ds_read_b128 v[210:213], v155 offset:54272
	ds_read_b128 v[214:217], v155 offset:55296
	ds_read_b128 v[218:221], v155 offset:56320
	global_load_lds_dwordx4 v[6:7], off
	s_add_i32 m0, s6, 0x2000
	s_add_u32 s0, s0, 0xc0080
	v_lshl_add_u64 v[6:7], v[224:225], 0, s[24:25]
	s_addc_u32 s1, s1, 0
	s_add_i32 s6, s9, s41
	global_load_lds_dwordx4 v[6:7], off
	v_lshl_add_u64 v[6:7], s[0:1], 0, v[132:133]
	s_mov_b32 m0, s6
	s_nop 0
	global_load_lds_dwordx4 v[6:7], off
	v_lshl_add_u64 v[6:7], s[0:1], 0, v[134:135]
	s_add_i32 m0, s6, 0x2000
	s_nop 0
	global_load_lds_dwordx4 v[6:7], off
	v_lshl_add_u64 v[6:7], v[226:227], 0, s[24:25]
	s_mov_b32 m0, s47
	s_nop 0
	global_load_lds_dwordx4 v[6:7], off
	v_lshl_add_u64 v[6:7], v[228:229], 0, s[24:25]
	s_mov_b32 m0, s48
	s_nop 0
	global_load_lds_dwordx4 v[6:7], off
	s_waitcnt vmcnt(8)
	s_waitcnt lgkmcnt(0)
	s_setprio 1
	s_barrier
	s_waitcnt lgkmcnt(0)
	v_mfma_f32_16x16x32_bf16 v[64:67], v[156:159], v[190:193], v[64:67]
	v_mfma_f32_16x16x32_bf16 v[60:63], v[164:167], v[190:193], v[60:63]
	v_mfma_f32_16x16x32_bf16 v[48:51], v[156:159], v[198:201], v[48:51]
	v_mfma_f32_16x16x32_bf16 v[44:47], v[164:167], v[198:201], v[44:47]
	v_mfma_f32_16x16x32_bf16 v[32:35], v[156:159], v[206:209], v[32:35]
	v_mfma_f32_16x16x32_bf16 v[28:31], v[164:167], v[206:209], v[28:31]
	v_mfma_f32_16x16x32_bf16 v[16:19], v[156:159], v[214:217], v[16:19]
	v_mfma_f32_16x16x32_bf16 v[12:15], v[164:167], v[214:217], v[12:15]
	v_mfma_f32_16x16x32_bf16 v[64:67], v[160:163], v[194:197], v[64:67]
	v_mfma_f32_16x16x32_bf16 v[60:63], v[168:171], v[194:197], v[60:63]
	v_mfma_f32_16x16x32_bf16 v[48:51], v[160:163], v[202:205], v[48:51]
	v_mfma_f32_16x16x32_bf16 v[44:47], v[168:171], v[202:205], v[44:47]
	v_mfma_f32_16x16x32_bf16 v[32:35], v[160:163], v[210:213], v[32:35]
	v_mfma_f32_16x16x32_bf16 v[28:31], v[168:171], v[210:213], v[28:31]
	v_mfma_f32_16x16x32_bf16 v[16:19], v[160:163], v[218:221], v[16:19]
	v_mfma_f32_16x16x32_bf16 v[12:15], v[168:171], v[218:221], v[12:15]
	s_setprio 0
	s_setprio 1
	v_mfma_f32_16x16x32_bf16 v[56:59], v[174:177], v[190:193], v[56:59]
	v_mfma_f32_16x16x32_bf16 v[52:55], v[182:185], v[190:193], v[52:55]
	v_mfma_f32_16x16x32_bf16 v[40:43], v[174:177], v[198:201], v[40:43]
	v_mfma_f32_16x16x32_bf16 v[36:39], v[182:185], v[198:201], v[36:39]
	v_mfma_f32_16x16x32_bf16 v[24:27], v[174:177], v[206:209], v[24:27]
	v_mfma_f32_16x16x32_bf16 v[20:23], v[182:185], v[206:209], v[20:23]
	v_mfma_f32_16x16x32_bf16 v[6:9], v[174:177], v[214:217], v[8:11]
	v_mfma_f32_16x16x32_bf16 v[2:5], v[182:185], v[214:217], v[2:5]
	v_mfma_f32_16x16x32_bf16 v[56:59], v[178:181], v[194:197], v[56:59]
	v_mfma_f32_16x16x32_bf16 v[52:55], v[186:189], v[194:197], v[52:55]
	v_mfma_f32_16x16x32_bf16 v[40:43], v[178:181], v[202:205], v[40:43]
	v_mfma_f32_16x16x32_bf16 v[36:39], v[186:189], v[202:205], v[36:39]
	v_mfma_f32_16x16x32_bf16 v[24:27], v[178:181], v[210:213], v[24:27]
	v_mfma_f32_16x16x32_bf16 v[20:23], v[186:189], v[210:213], v[20:23]
	v_mfma_f32_16x16x32_bf16 v[8:11], v[178:181], v[218:221], v[6:9]
	v_mfma_f32_16x16x32_bf16 v[4:7], v[186:189], v[218:221], v[2:5]
	s_barrier
	s_setprio 0
	s_add_i32 s62, s62, 2
	s_add_u32 s38, s38, 0x100
	s_addc_u32 s39, s39, 0
	s_cmp_gt_u32 s62, 45
	s_cbranch_scc1 .LBB0_626

.LBB0_769:
	ds_read_b128 v[144:147], v151
	ds_read_b128 v[156:159], v151 offset:1024
	ds_read_b128 v[160:163], v151 offset:2048
	ds_read_b128 v[164:167], v151 offset:3072
	ds_read_b128 v[168:171], v152
	ds_read_b128 v[174:177], v152 offset:1024
	ds_read_b128 v[178:181], v152 offset:2048
	ds_read_b128 v[182:185], v152 offset:3072
	s_add_u32 s38, s34, 0xfff80080
	s_addc_u32 s39, s35, -1
	s_cmp_eq_u32 s67, 28
	s_cselect_b32 s41, s27, s39
	s_cselect_b32 s40, s63, s38
	s_cselect_b32 s39, s25, s66
	s_cselect_b32 s38, s64, s65
	v_lshl_add_u64 v[218:219], s[34:35], 0, v[136:137]
	s_add_i32 m0, s47, 0xc000
	ds_read_b128 v[186:189], v153
	ds_read_b128 v[190:193], v153 offset:1024
	ds_read_b128 v[194:197], v153 offset:2048
	ds_read_b128 v[198:201], v153 offset:3072
	ds_read_b128 v[202:205], v153 offset:4096
	ds_read_b128 v[206:209], v153 offset:5120
	ds_read_b128 v[210:213], v153 offset:6144
	ds_read_b128 v[214:217], v153 offset:7168
	global_load_lds_dwordx4 v[218:219], off
	v_lshl_add_u64 v[218:219], s[34:35], 0, v[138:139]
	s_add_i32 m0, s47, 0xe000
	s_nop 0
	global_load_lds_dwordx4 v[218:219], off
	s_waitcnt vmcnt(8)
	s_waitcnt lgkmcnt(0)
	s_setprio 1
	s_barrier
	s_waitcnt lgkmcnt(0)
	v_mfma_f32_16x16x32_bf16 v[124:127], v[144:147], v[186:189], v[124:127]
	v_mfma_f32_16x16x32_bf16 v[120:123], v[160:163], v[186:189], v[120:123]
	v_mfma_f32_16x16x32_bf16 v[108:111], v[144:147], v[194:197], v[108:111]
	v_mfma_f32_16x16x32_bf16 v[104:107], v[160:163], v[194:197], v[104:107]
	v_mfma_f32_16x16x32_bf16 v[92:95], v[144:147], v[202:205], v[92:95]
	v_mfma_f32_16x16x32_bf16 v[88:91], v[160:163], v[202:205], v[88:91]
	v_mfma_f32_16x16x32_bf16 v[80:83], v[144:147], v[210:213], v[80:83]
	v_mfma_f32_16x16x32_bf16 v[72:75], v[160:163], v[210:213], v[72:75]
	v_mfma_f32_16x16x32_bf16 v[124:127], v[156:159], v[190:193], v[124:127]
	v_mfma_f32_16x16x32_bf16 v[120:123], v[164:167], v[190:193], v[120:123]
	v_mfma_f32_16x16x32_bf16 v[108:111], v[156:159], v[198:201], v[108:111]
	v_mfma_f32_16x16x32_bf16 v[104:107], v[164:167], v[198:201], v[104:107]
	v_mfma_f32_16x16x32_bf16 v[92:95], v[156:159], v[206:209], v[92:95]
	v_mfma_f32_16x16x32_bf16 v[88:91], v[164:167], v[206:209], v[88:91]
	v_mfma_f32_16x16x32_bf16 v[80:83], v[156:159], v[214:217], v[80:83]
	v_mfma_f32_16x16x32_bf16 v[72:75], v[164:167], v[214:217], v[72:75]
	s_setprio 0
	s_setprio 1
	v_mfma_f32_16x16x32_bf16 v[116:119], v[168:171], v[186:189], v[116:119]
	v_mfma_f32_16x16x32_bf16 v[112:115], v[178:181], v[186:189], v[112:115]
	v_mfma_f32_16x16x32_bf16 v[100:103], v[168:171], v[194:197], v[100:103]
	v_mfma_f32_16x16x32_bf16 v[96:99], v[178:181], v[194:197], v[96:99]
	v_mfma_f32_16x16x32_bf16 v[84:87], v[168:171], v[202:205], v[84:87]
	v_mfma_f32_16x16x32_bf16 v[76:79], v[178:181], v[202:205], v[76:79]
	v_mfma_f32_16x16x32_bf16 v[68:71], v[168:171], v[210:213], v[68:71]
	v_mfma_f32_16x16x32_bf16 v[64:67], v[178:181], v[210:213], v[64:67]
	v_mfma_f32_16x16x32_bf16 v[116:119], v[174:177], v[190:193], v[116:119]
	v_mfma_f32_16x16x32_bf16 v[112:115], v[182:185], v[190:193], v[112:115]
	v_mfma_f32_16x16x32_bf16 v[100:103], v[174:177], v[198:201], v[100:103]
	v_mfma_f32_16x16x32_bf16 v[96:99], v[182:185], v[198:201], v[96:99]
	v_mfma_f32_16x16x32_bf16 v[84:87], v[174:177], v[206:209], v[84:87]
	v_mfma_f32_16x16x32_bf16 v[76:79], v[182:185], v[206:209], v[76:79]
	v_mfma_f32_16x16x32_bf16 v[68:71], v[174:177], v[214:217], v[68:71]
	v_mfma_f32_16x16x32_bf16 v[64:67], v[182:185], v[214:217], v[64:67]
	s_barrier
	s_setprio 0
	s_add_i32 s68, s56, s46
	v_lshl_add_u64 v[218:219], s[38:39], 0, v[130:131]
	s_mov_b32 m0, s68
	ds_read_b128 v[186:189], v153 offset:16384
	ds_read_b128 v[190:193], v153 offset:17408
	ds_read_b128 v[194:197], v153 offset:18432
	ds_read_b128 v[198:201], v153 offset:19456
	ds_read_b128 v[202:205], v153 offset:20480
	ds_read_b128 v[206:209], v153 offset:21504
	ds_read_b128 v[210:213], v153 offset:22528
	ds_read_b128 v[214:217], v153 offset:23552
	global_load_lds_dwordx4 v[218:219], off
	s_add_i32 m0, s68, 0x2000
	s_add_u32 s68, s38, 0x80000
	v_lshl_add_u64 v[220:221], s[38:39], 0, v[134:135]
	s_addc_u32 s69, s39, 0
	s_add_i32 s70, s57, s46
	global_load_lds_dwordx4 v[220:221], off
	v_lshl_add_u64 v[222:223], s[68:69], 0, v[130:131]
	s_mov_b32 m0, s70
	v_lshl_add_u64 v[224:225], s[40:41], 0, v[132:133]
	global_load_lds_dwordx4 v[222:223], off
	v_lshl_add_u64 v[222:223], s[68:69], 0, v[134:135]
	s_add_i32 m0, s70, 0x2000
	s_nop 0
	global_load_lds_dwordx4 v[222:223], off
	v_lshl_add_u64 v[222:223], s[40:41], 0, v[128:129]
	s_mov_b32 m0, s47
	s_nop 0
	global_load_lds_dwordx4 v[222:223], off
	s_mov_b32 m0, s48
	s_nop 0
	global_load_lds_dwordx4 v[224:225], off
	s_waitcnt vmcnt(8)
	s_waitcnt lgkmcnt(0)
	s_setprio 1
	s_barrier
	s_waitcnt lgkmcnt(0)
	v_mfma_f32_16x16x32_bf16 v[60:63], v[144:147], v[186:189], v[60:63]
	v_mfma_f32_16x16x32_bf16 v[56:59], v[160:163], v[186:189], v[56:59]
	v_mfma_f32_16x16x32_bf16 v[44:47], v[144:147], v[194:197], v[44:47]
	v_mfma_f32_16x16x32_bf16 v[40:43], v[160:163], v[194:197], v[40:43]
	v_mfma_f32_16x16x32_bf16 v[28:31], v[144:147], v[202:205], v[28:31]
	v_mfma_f32_16x16x32_bf16 v[24:27], v[160:163], v[202:205], v[24:27]
	v_mfma_f32_16x16x32_bf16 v[12:15], v[144:147], v[210:213], v[12:15]
	v_mfma_f32_16x16x32_bf16 v[8:11], v[160:163], v[210:213], v[8:11]
	v_mfma_f32_16x16x32_bf16 v[60:63], v[156:159], v[190:193], v[60:63]
	v_mfma_f32_16x16x32_bf16 v[56:59], v[164:167], v[190:193], v[56:59]
	v_mfma_f32_16x16x32_bf16 v[44:47], v[156:159], v[198:201], v[44:47]
	v_mfma_f32_16x16x32_bf16 v[40:43], v[164:167], v[198:201], v[40:43]
	v_mfma_f32_16x16x32_bf16 v[28:31], v[156:159], v[206:209], v[28:31]
	v_mfma_f32_16x16x32_bf16 v[24:27], v[164:167], v[206:209], v[24:27]
	v_mfma_f32_16x16x32_bf16 v[12:15], v[156:159], v[214:217], v[12:15]
	v_mfma_f32_16x16x32_bf16 v[8:11], v[164:167], v[214:217], v[8:11]
	s_setprio 0
	s_setprio 1
	v_mfma_f32_16x16x32_bf16 v[52:55], v[168:171], v[186:189], v[52:55]
	v_mfma_f32_16x16x32_bf16 v[48:51], v[178:181], v[186:189], v[48:51]
	v_mfma_f32_16x16x32_bf16 v[36:39], v[168:171], v[194:197], v[36:39]
	v_mfma_f32_16x16x32_bf16 v[32:35], v[178:181], v[194:197], v[32:35]
	v_mfma_f32_16x16x32_bf16 v[20:23], v[168:171], v[202:205], v[20:23]
	v_mfma_f32_16x16x32_bf16 v[16:19], v[178:181], v[202:205], v[16:19]
	v_mfma_f32_16x16x32_bf16 v[4:7], v[168:171], v[210:213], v[4:7]
	v_mfma_f32_16x16x32_bf16 v[0:3], v[178:181], v[210:213], v[0:3]
	v_mfma_f32_16x16x32_bf16 v[52:55], v[174:177], v[190:193], v[52:55]
	v_mfma_f32_16x16x32_bf16 v[48:51], v[182:185], v[190:193], v[48:51]
	v_mfma_f32_16x16x32_bf16 v[36:39], v[174:177], v[198:201], v[36:39]
	v_mfma_f32_16x16x32_bf16 v[32:35], v[182:185], v[198:201], v[32:35]
	v_mfma_f32_16x16x32_bf16 v[20:23], v[174:177], v[206:209], v[20:23]
	v_mfma_f32_16x16x32_bf16 v[16:19], v[182:185], v[206:209], v[16:19]
	v_mfma_f32_16x16x32_bf16 v[4:7], v[174:177], v[214:217], v[4:7]
	v_mfma_f32_16x16x32_bf16 v[0:3], v[182:185], v[214:217], v[0:3]
	s_barrier
	s_setprio 0
	s_add_i32 s68, 0, 0x18000
	v_add_u32_e32 v155, s68, v149
	s_add_i32 s69, 0, 0x1c000
	ds_read_b128 v[144:147], v155
	ds_read_b128 v[156:159], v155 offset:1024
	ds_read_b128 v[160:163], v155 offset:2048
	ds_read_b128 v[164:167], v155 offset:3072
	v_add_u32_e32 v155, s69, v149
	ds_read_b128 v[168:171], v155
	ds_read_b128 v[174:177], v155 offset:1024
	ds_read_b128 v[178:181], v155 offset:2048
	ds_read_b128 v[182:185], v155 offset:3072
	s_add_u32 s40, s40, 0x80000
	s_addc_u32 s41, s41, 0
	s_mov_b32 m0, s49
	v_lshl_add_u64 v[226:227], s[40:41], 0, v[128:129]
	ds_read_b128 v[186:189], v153 offset:32768
	ds_read_b128 v[190:193], v153 offset:33792
	ds_read_b128 v[194:197], v153 offset:34816
	ds_read_b128 v[198:201], v153 offset:35840
	ds_read_b128 v[202:205], v153 offset:36864
	ds_read_b128 v[206:209], v153 offset:37888
	ds_read_b128 v[210:213], v153 offset:38912
	ds_read_b128 v[214:217], v153 offset:39936
	global_load_lds_dwordx4 v[226:227], off
	v_lshl_add_u64 v[226:227], s[40:41], 0, v[132:133]
	s_mov_b32 m0, s50
	s_nop 0
	global_load_lds_dwordx4 v[226:227], off
	s_waitcnt vmcnt(8)
	s_waitcnt lgkmcnt(0)
	s_setprio 1
	s_barrier
	s_waitcnt lgkmcnt(0)
	v_mfma_f32_16x16x32_bf16 v[124:127], v[144:147], v[186:189], v[124:127]
	v_mfma_f32_16x16x32_bf16 v[120:123], v[160:163], v[186:189], v[120:123]
	v_mfma_f32_16x16x32_bf16 v[108:111], v[144:147], v[194:197], v[108:111]
	v_mfma_f32_16x16x32_bf16 v[104:107], v[160:163], v[194:197], v[104:107]
	v_mfma_f32_16x16x32_bf16 v[92:95], v[144:147], v[202:205], v[92:95]
	v_mfma_f32_16x16x32_bf16 v[88:91], v[160:163], v[202:205], v[88:91]
	v_mfma_f32_16x16x32_bf16 v[80:83], v[144:147], v[210:213], v[80:83]
	v_mfma_f32_16x16x32_bf16 v[72:75], v[160:163], v[210:213], v[72:75]
	v_mfma_f32_16x16x32_bf16 v[124:127], v[156:159], v[190:193], v[124:127]
	v_mfma_f32_16x16x32_bf16 v[120:123], v[164:167], v[190:193], v[120:123]
	v_mfma_f32_16x16x32_bf16 v[108:111], v[156:159], v[198:201], v[108:111]
	v_mfma_f32_16x16x32_bf16 v[104:107], v[164:167], v[198:201], v[104:107]
	v_mfma_f32_16x16x32_bf16 v[92:95], v[156:159], v[206:209], v[92:95]
	v_mfma_f32_16x16x32_bf16 v[88:91], v[164:167], v[206:209], v[88:91]
	v_mfma_f32_16x16x32_bf16 v[80:83], v[156:159], v[214:217], v[80:83]
	v_mfma_f32_16x16x32_bf16 v[72:75], v[164:167], v[214:217], v[72:75]
	s_setprio 0
	s_setprio 1
	v_mfma_f32_16x16x32_bf16 v[116:119], v[168:171], v[186:189], v[116:119]
	v_mfma_f32_16x16x32_bf16 v[112:115], v[178:181], v[186:189], v[112:115]
	v_mfma_f32_16x16x32_bf16 v[100:103], v[168:171], v[194:197], v[100:103]
	v_mfma_f32_16x16x32_bf16 v[96:99], v[178:181], v[194:197], v[96:99]
	v_mfma_f32_16x16x32_bf16 v[84:87], v[168:171], v[202:205], v[84:87]
	v_mfma_f32_16x16x32_bf16 v[76:79], v[178:181], v[202:205], v[76:79]
	v_mfma_f32_16x16x32_bf16 v[68:71], v[168:171], v[210:213], v[68:71]
	v_mfma_f32_16x16x32_bf16 v[64:67], v[178:181], v[210:213], v[64:67]
	v_mfma_f32_16x16x32_bf16 v[116:119], v[174:177], v[190:193], v[116:119]
	v_mfma_f32_16x16x32_bf16 v[112:115], v[182:185], v[190:193], v[112:115]
	v_mfma_f32_16x16x32_bf16 v[100:103], v[174:177], v[198:201], v[100:103]
	v_mfma_f32_16x16x32_bf16 v[96:99], v[182:185], v[198:201], v[96:99]
	v_mfma_f32_16x16x32_bf16 v[84:87], v[174:177], v[206:209], v[84:87]
	v_mfma_f32_16x16x32_bf16 v[76:79], v[182:185], v[206:209], v[76:79]
	v_mfma_f32_16x16x32_bf16 v[68:71], v[174:177], v[214:217], v[68:71]
	v_mfma_f32_16x16x32_bf16 v[64:67], v[182:185], v[214:217], v[64:67]
	s_barrier
	s_setprio 0
	s_add_i32 s40, s68, s46
	v_lshl_add_u64 v[218:219], v[218:219], 0, s[12:13]
	s_mov_b32 m0, s40
	ds_read_b128 v[186:189], v153 offset:49152
	ds_read_b128 v[190:193], v153 offset:50176
	ds_read_b128 v[194:197], v153 offset:51200
	ds_read_b128 v[198:201], v153 offset:52224
	ds_read_b128 v[202:205], v153 offset:53248
	ds_read_b128 v[206:209], v153 offset:54272
	ds_read_b128 v[210:213], v153 offset:55296
	ds_read_b128 v[214:217], v153 offset:56320
	global_load_lds_dwordx4 v[218:219], off
	s_add_i32 m0, s40, 0x2000
	s_add_u32 s38, s38, 0x80080
	v_lshl_add_u64 v[218:219], v[220:221], 0, s[12:13]
	s_addc_u32 s39, s39, 0
	s_add_i32 s40, s69, s46
	global_load_lds_dwordx4 v[218:219], off
	v_lshl_add_u64 v[218:219], s[38:39], 0, v[130:131]
	s_mov_b32 m0, s40
	s_nop 0
	global_load_lds_dwordx4 v[218:219], off
	v_lshl_add_u64 v[218:219], s[38:39], 0, v[134:135]
	s_add_i32 m0, s40, 0x2000
	s_nop 0
	global_load_lds_dwordx4 v[218:219], off
	v_lshl_add_u64 v[218:219], v[222:223], 0, s[12:13]
	s_mov_b32 m0, s52
	s_nop 0
	global_load_lds_dwordx4 v[218:219], off
	v_lshl_add_u64 v[218:219], v[224:225], 0, s[12:13]
	s_mov_b32 m0, s53
	s_nop 0
	global_load_lds_dwordx4 v[218:219], off
	s_waitcnt vmcnt(8)
	s_waitcnt lgkmcnt(0)
	s_setprio 1
	s_barrier
	s_waitcnt lgkmcnt(0)
	v_mfma_f32_16x16x32_bf16 v[60:63], v[144:147], v[186:189], v[60:63]
	v_mfma_f32_16x16x32_bf16 v[56:59], v[160:163], v[186:189], v[56:59]
	v_mfma_f32_16x16x32_bf16 v[44:47], v[144:147], v[194:197], v[44:47]
	v_mfma_f32_16x16x32_bf16 v[40:43], v[160:163], v[194:197], v[40:43]
	v_mfma_f32_16x16x32_bf16 v[28:31], v[144:147], v[202:205], v[28:31]
	v_mfma_f32_16x16x32_bf16 v[24:27], v[160:163], v[202:205], v[24:27]
	v_mfma_f32_16x16x32_bf16 v[12:15], v[144:147], v[210:213], v[12:15]
	v_mfma_f32_16x16x32_bf16 v[8:11], v[160:163], v[210:213], v[8:11]
	v_mfma_f32_16x16x32_bf16 v[60:63], v[156:159], v[190:193], v[60:63]
	v_mfma_f32_16x16x32_bf16 v[56:59], v[164:167], v[190:193], v[56:59]
	v_mfma_f32_16x16x32_bf16 v[44:47], v[156:159], v[198:201], v[44:47]
	v_mfma_f32_16x16x32_bf16 v[40:43], v[164:167], v[198:201], v[40:43]
	v_mfma_f32_16x16x32_bf16 v[28:31], v[156:159], v[206:209], v[28:31]
	v_mfma_f32_16x16x32_bf16 v[24:27], v[164:167], v[206:209], v[24:27]
	v_mfma_f32_16x16x32_bf16 v[12:15], v[156:159], v[214:217], v[12:15]
	v_mfma_f32_16x16x32_bf16 v[8:11], v[164:167], v[214:217], v[8:11]
	s_setprio 0
	s_setprio 1
	v_mfma_f32_16x16x32_bf16 v[52:55], v[168:171], v[186:189], v[52:55]
	v_mfma_f32_16x16x32_bf16 v[48:51], v[178:181], v[186:189], v[48:51]
	v_mfma_f32_16x16x32_bf16 v[36:39], v[168:171], v[194:197], v[36:39]
	v_mfma_f32_16x16x32_bf16 v[32:35], v[178:181], v[194:197], v[32:35]
	v_mfma_f32_16x16x32_bf16 v[20:23], v[168:171], v[202:205], v[20:23]
	v_mfma_f32_16x16x32_bf16 v[16:19], v[178:181], v[202:205], v[16:19]
	v_mfma_f32_16x16x32_bf16 v[4:7], v[168:171], v[210:213], v[4:7]
	v_mfma_f32_16x16x32_bf16 v[0:3], v[178:181], v[210:213], v[0:3]
	v_mfma_f32_16x16x32_bf16 v[52:55], v[174:177], v[190:193], v[52:55]
	v_mfma_f32_16x16x32_bf16 v[48:51], v[182:185], v[190:193], v[48:51]
	v_mfma_f32_16x16x32_bf16 v[36:39], v[174:177], v[198:201], v[36:39]
	v_mfma_f32_16x16x32_bf16 v[32:35], v[182:185], v[198:201], v[32:35]
	v_mfma_f32_16x16x32_bf16 v[20:23], v[174:177], v[206:209], v[20:23]
	v_mfma_f32_16x16x32_bf16 v[16:19], v[182:185], v[206:209], v[16:19]
	v_mfma_f32_16x16x32_bf16 v[4:7], v[174:177], v[214:217], v[4:7]
	v_mfma_f32_16x16x32_bf16 v[0:3], v[182:185], v[214:217], v[0:3]
	s_barrier
	s_setprio 0
	s_add_i32 s67, s67, 2
	s_add_u32 s34, s34, 0x100
	s_addc_u32 s35, s35, 0
	s_add_u32 s65, s65, 0x100
	s_addc_u32 s66, s66, 0
	s_cmp_gt_u32 s67, 29
	s_cbranch_scc0 .LBB0_769
	s_and_b64 vcc, exec, s[14:15]
	s_cbranch_vccz .LBB0_772
	s_barrier

.LBB0_976:
	ds_read_b128 v[140:143], v148
	ds_read_b128 v[152:155], v148 offset:1024
	ds_read_b128 v[156:159], v148 offset:2048
	ds_read_b128 v[160:163], v148 offset:3072
	ds_read_b128 v[164:167], v149
	ds_read_b128 v[168:171], v149 offset:1024
	ds_read_b128 v[174:177], v149 offset:2048
	ds_read_b128 v[178:181], v149 offset:3072
	s_add_u32 s40, s38, 0xfffe0080
	s_addc_u32 s41, s39, -1
	s_cmp_eq_u32 s59, 4
	s_cselect_b32 s43, s25, s41
	s_cselect_b32 s42, s31, s40
	s_cselect_b32 s41, s23, s58
	s_cselect_b32 s40, s56, s57
	v_lshl_add_u64 v[214:215], s[38:39], 0, v[132:133]
	s_add_i32 m0, s35, 0xc000
	ds_read_b128 v[182:185], v150
	ds_read_b128 v[186:189], v150 offset:1024
	ds_read_b128 v[190:193], v150 offset:2048
	ds_read_b128 v[194:197], v150 offset:3072
	ds_read_b128 v[198:201], v150 offset:4096
	ds_read_b128 v[202:205], v150 offset:5120
	ds_read_b128 v[206:209], v150 offset:6144
	ds_read_b128 v[210:213], v150 offset:7168
	global_load_lds_dwordx4 v[214:215], off
	v_lshl_add_u64 v[214:215], s[38:39], 0, v[134:135]
	s_add_i32 m0, s35, 0xe000
	s_nop 0
	global_load_lds_dwordx4 v[214:215], off
	s_waitcnt vmcnt(8)
	s_waitcnt lgkmcnt(0)
	s_setprio 1
	s_barrier
	s_waitcnt lgkmcnt(0)
	v_mfma_f32_16x16x32_bf16 v[124:127], v[140:143], v[182:185], v[124:127]
	v_mfma_f32_16x16x32_bf16 v[120:123], v[156:159], v[182:185], v[120:123]
	v_mfma_f32_16x16x32_bf16 v[108:111], v[140:143], v[190:193], v[108:111]
	v_mfma_f32_16x16x32_bf16 v[104:107], v[156:159], v[190:193], v[104:107]
	v_mfma_f32_16x16x32_bf16 v[92:95], v[140:143], v[198:201], v[92:95]
	v_mfma_f32_16x16x32_bf16 v[88:91], v[156:159], v[198:201], v[88:91]
	v_mfma_f32_16x16x32_bf16 v[76:79], v[140:143], v[206:209], v[76:79]
	v_mfma_f32_16x16x32_bf16 v[72:75], v[156:159], v[206:209], v[72:75]
	v_mfma_f32_16x16x32_bf16 v[124:127], v[152:155], v[186:189], v[124:127]
	v_mfma_f32_16x16x32_bf16 v[120:123], v[160:163], v[186:189], v[120:123]
	v_mfma_f32_16x16x32_bf16 v[108:111], v[152:155], v[194:197], v[108:111]
	v_mfma_f32_16x16x32_bf16 v[104:107], v[160:163], v[194:197], v[104:107]
	v_mfma_f32_16x16x32_bf16 v[92:95], v[152:155], v[202:205], v[92:95]
	v_mfma_f32_16x16x32_bf16 v[88:91], v[160:163], v[202:205], v[88:91]
	v_mfma_f32_16x16x32_bf16 v[76:79], v[152:155], v[210:213], v[76:79]
	v_mfma_f32_16x16x32_bf16 v[72:75], v[160:163], v[210:213], v[72:75]
	s_setprio 0
	s_setprio 1
	v_mfma_f32_16x16x32_bf16 v[116:119], v[164:167], v[182:185], v[116:119]
	v_mfma_f32_16x16x32_bf16 v[112:115], v[174:177], v[182:185], v[112:115]
	v_mfma_f32_16x16x32_bf16 v[100:103], v[164:167], v[190:193], v[100:103]
	v_mfma_f32_16x16x32_bf16 v[96:99], v[174:177], v[190:193], v[96:99]
	v_mfma_f32_16x16x32_bf16 v[84:87], v[164:167], v[198:201], v[84:87]
	v_mfma_f32_16x16x32_bf16 v[80:83], v[174:177], v[198:201], v[80:83]
	v_mfma_f32_16x16x32_bf16 v[68:71], v[164:167], v[206:209], v[68:71]
	v_mfma_f32_16x16x32_bf16 v[64:67], v[174:177], v[206:209], v[64:67]
	v_mfma_f32_16x16x32_bf16 v[116:119], v[168:171], v[186:189], v[116:119]
	v_mfma_f32_16x16x32_bf16 v[112:115], v[178:181], v[186:189], v[112:115]
	v_mfma_f32_16x16x32_bf16 v[100:103], v[168:171], v[194:197], v[100:103]
	v_mfma_f32_16x16x32_bf16 v[96:99], v[178:181], v[194:197], v[96:99]
	v_mfma_f32_16x16x32_bf16 v[84:87], v[168:171], v[202:205], v[84:87]
	v_mfma_f32_16x16x32_bf16 v[80:83], v[178:181], v[202:205], v[80:83]
	v_mfma_f32_16x16x32_bf16 v[68:71], v[168:171], v[210:213], v[68:71]
	v_mfma_f32_16x16x32_bf16 v[64:67], v[178:181], v[210:213], v[64:67]
	s_barrier
	s_setprio 0
	s_add_i32 s60, s53, s33
	v_lshl_add_u64 v[214:215], s[40:41], 0, v[128:129]
	s_mov_b32 m0, s60
	ds_read_b128 v[182:185], v150 offset:16384
	ds_read_b128 v[186:189], v150 offset:17408
	ds_read_b128 v[190:193], v150 offset:18432
	ds_read_b128 v[194:197], v150 offset:19456
	ds_read_b128 v[198:201], v150 offset:20480
	ds_read_b128 v[202:205], v150 offset:21504
	ds_read_b128 v[206:209], v150 offset:22528
	ds_read_b128 v[210:213], v150 offset:23552
	global_load_lds_dwordx4 v[214:215], off
	s_add_i32 m0, s60, 0x2000
	s_add_u32 s60, s40, 0x20000
	v_lshl_add_u64 v[216:217], s[40:41], 0, v[130:131]
	s_addc_u32 s61, s41, 0
	s_add_i32 s62, s54, s33
	global_load_lds_dwordx4 v[216:217], off
	v_lshl_add_u64 v[218:219], s[60:61], 0, v[128:129]
	s_mov_b32 m0, s62
	v_lshl_add_u64 v[220:221], s[42:43], 0, v[130:131]
	global_load_lds_dwordx4 v[218:219], off
	v_lshl_add_u64 v[218:219], s[60:61], 0, v[130:131]
	s_add_i32 m0, s62, 0x2000
	s_nop 0
	global_load_lds_dwordx4 v[218:219], off
	v_lshl_add_u64 v[218:219], s[42:43], 0, v[128:129]
	s_mov_b32 m0, s35
	s_nop 0
	global_load_lds_dwordx4 v[218:219], off
	s_mov_b32 m0, s44
	s_nop 0
	global_load_lds_dwordx4 v[220:221], off
	s_waitcnt vmcnt(8)
	s_waitcnt lgkmcnt(0)
	s_setprio 1
	s_barrier
	s_waitcnt lgkmcnt(0)
	v_mfma_f32_16x16x32_bf16 v[60:63], v[140:143], v[182:185], v[60:63]
	v_mfma_f32_16x16x32_bf16 v[56:59], v[156:159], v[182:185], v[56:59]
	v_mfma_f32_16x16x32_bf16 v[44:47], v[140:143], v[190:193], v[44:47]
	v_mfma_f32_16x16x32_bf16 v[40:43], v[156:159], v[190:193], v[40:43]
	v_mfma_f32_16x16x32_bf16 v[28:31], v[140:143], v[198:201], v[28:31]
	v_mfma_f32_16x16x32_bf16 v[24:27], v[156:159], v[198:201], v[24:27]
	v_mfma_f32_16x16x32_bf16 v[12:15], v[140:143], v[206:209], v[12:15]
	v_mfma_f32_16x16x32_bf16 v[8:11], v[156:159], v[206:209], v[8:11]
	v_mfma_f32_16x16x32_bf16 v[60:63], v[152:155], v[186:189], v[60:63]
	v_mfma_f32_16x16x32_bf16 v[56:59], v[160:163], v[186:189], v[56:59]
	v_mfma_f32_16x16x32_bf16 v[44:47], v[152:155], v[194:197], v[44:47]
	v_mfma_f32_16x16x32_bf16 v[40:43], v[160:163], v[194:197], v[40:43]
	v_mfma_f32_16x16x32_bf16 v[28:31], v[152:155], v[202:205], v[28:31]
	v_mfma_f32_16x16x32_bf16 v[24:27], v[160:163], v[202:205], v[24:27]
	v_mfma_f32_16x16x32_bf16 v[12:15], v[152:155], v[210:213], v[12:15]
	v_mfma_f32_16x16x32_bf16 v[8:11], v[160:163], v[210:213], v[8:11]
	s_setprio 0
	s_setprio 1
	v_mfma_f32_16x16x32_bf16 v[52:55], v[164:167], v[182:185], v[52:55]
	v_mfma_f32_16x16x32_bf16 v[48:51], v[174:177], v[182:185], v[48:51]
	v_mfma_f32_16x16x32_bf16 v[36:39], v[164:167], v[190:193], v[36:39]
	v_mfma_f32_16x16x32_bf16 v[32:35], v[174:177], v[190:193], v[32:35]
	v_mfma_f32_16x16x32_bf16 v[20:23], v[164:167], v[198:201], v[20:23]
	v_mfma_f32_16x16x32_bf16 v[16:19], v[174:177], v[198:201], v[16:19]
	v_mfma_f32_16x16x32_bf16 v[4:7], v[164:167], v[206:209], v[4:7]
	v_mfma_f32_16x16x32_bf16 v[0:3], v[174:177], v[206:209], v[0:3]
	v_mfma_f32_16x16x32_bf16 v[52:55], v[168:171], v[186:189], v[52:55]
	v_mfma_f32_16x16x32_bf16 v[48:51], v[178:181], v[186:189], v[48:51]
	v_mfma_f32_16x16x32_bf16 v[36:39], v[168:171], v[194:197], v[36:39]
	v_mfma_f32_16x16x32_bf16 v[32:35], v[178:181], v[194:197], v[32:35]
	v_mfma_f32_16x16x32_bf16 v[20:23], v[168:171], v[202:205], v[20:23]
	v_mfma_f32_16x16x32_bf16 v[16:19], v[178:181], v[202:205], v[16:19]
	v_mfma_f32_16x16x32_bf16 v[4:7], v[168:171], v[210:213], v[4:7]
	v_mfma_f32_16x16x32_bf16 v[0:3], v[178:181], v[210:213], v[0:3]
	s_barrier
	s_setprio 0
	s_add_i32 s60, 0, 0x18000
	v_add_u32_e32 v151, s60, v146
	s_add_i32 s61, 0, 0x1c000
	ds_read_b128 v[140:143], v151
	ds_read_b128 v[152:155], v151 offset:1024
	ds_read_b128 v[156:159], v151 offset:2048
	ds_read_b128 v[160:163], v151 offset:3072
	v_add_u32_e32 v151, s61, v146
	ds_read_b128 v[164:167], v151
	ds_read_b128 v[168:171], v151 offset:1024
	ds_read_b128 v[174:177], v151 offset:2048
	ds_read_b128 v[178:181], v151 offset:3072
	s_add_u32 s42, s42, 0x20000
	s_addc_u32 s43, s43, 0
	s_mov_b32 m0, s45
	v_lshl_add_u64 v[222:223], s[42:43], 0, v[128:129]
	ds_read_b128 v[182:185], v150 offset:32768
	ds_read_b128 v[186:189], v150 offset:33792
	ds_read_b128 v[190:193], v150 offset:34816
	ds_read_b128 v[194:197], v150 offset:35840
	ds_read_b128 v[198:201], v150 offset:36864
	ds_read_b128 v[202:205], v150 offset:37888
	ds_read_b128 v[206:209], v150 offset:38912
	ds_read_b128 v[210:213], v150 offset:39936
	global_load_lds_dwordx4 v[222:223], off
	v_lshl_add_u64 v[222:223], s[42:43], 0, v[130:131]
	s_mov_b32 m0, s46
	s_nop 0
	global_load_lds_dwordx4 v[222:223], off
	s_waitcnt vmcnt(8)
	s_waitcnt lgkmcnt(0)
	s_setprio 1
	s_barrier
	s_waitcnt lgkmcnt(0)
	v_mfma_f32_16x16x32_bf16 v[124:127], v[140:143], v[182:185], v[124:127]
	v_mfma_f32_16x16x32_bf16 v[120:123], v[156:159], v[182:185], v[120:123]
	v_mfma_f32_16x16x32_bf16 v[108:111], v[140:143], v[190:193], v[108:111]
	v_mfma_f32_16x16x32_bf16 v[104:107], v[156:159], v[190:193], v[104:107]
	v_mfma_f32_16x16x32_bf16 v[92:95], v[140:143], v[198:201], v[92:95]
	v_mfma_f32_16x16x32_bf16 v[88:91], v[156:159], v[198:201], v[88:91]
	v_mfma_f32_16x16x32_bf16 v[76:79], v[140:143], v[206:209], v[76:79]
	v_mfma_f32_16x16x32_bf16 v[72:75], v[156:159], v[206:209], v[72:75]
	v_mfma_f32_16x16x32_bf16 v[124:127], v[152:155], v[186:189], v[124:127]
	v_mfma_f32_16x16x32_bf16 v[120:123], v[160:163], v[186:189], v[120:123]
	v_mfma_f32_16x16x32_bf16 v[108:111], v[152:155], v[194:197], v[108:111]
	v_mfma_f32_16x16x32_bf16 v[104:107], v[160:163], v[194:197], v[104:107]
	v_mfma_f32_16x16x32_bf16 v[92:95], v[152:155], v[202:205], v[92:95]
	v_mfma_f32_16x16x32_bf16 v[88:91], v[160:163], v[202:205], v[88:91]
	v_mfma_f32_16x16x32_bf16 v[76:79], v[152:155], v[210:213], v[76:79]
	v_mfma_f32_16x16x32_bf16 v[72:75], v[160:163], v[210:213], v[72:75]
	s_setprio 0
	s_setprio 1
	v_mfma_f32_16x16x32_bf16 v[116:119], v[164:167], v[182:185], v[116:119]
	v_mfma_f32_16x16x32_bf16 v[112:115], v[174:177], v[182:185], v[112:115]
	v_mfma_f32_16x16x32_bf16 v[100:103], v[164:167], v[190:193], v[100:103]
	v_mfma_f32_16x16x32_bf16 v[96:99], v[174:177], v[190:193], v[96:99]
	v_mfma_f32_16x16x32_bf16 v[84:87], v[164:167], v[198:201], v[84:87]
	v_mfma_f32_16x16x32_bf16 v[80:83], v[174:177], v[198:201], v[80:83]
	v_mfma_f32_16x16x32_bf16 v[68:71], v[164:167], v[206:209], v[68:71]
	v_mfma_f32_16x16x32_bf16 v[64:67], v[174:177], v[206:209], v[64:67]
	v_mfma_f32_16x16x32_bf16 v[116:119], v[168:171], v[186:189], v[116:119]
	v_mfma_f32_16x16x32_bf16 v[112:115], v[178:181], v[186:189], v[112:115]
	v_mfma_f32_16x16x32_bf16 v[100:103], v[168:171], v[194:197], v[100:103]
	v_mfma_f32_16x16x32_bf16 v[96:99], v[178:181], v[194:197], v[96:99]
	v_mfma_f32_16x16x32_bf16 v[84:87], v[168:171], v[202:205], v[84:87]
	v_mfma_f32_16x16x32_bf16 v[80:83], v[178:181], v[202:205], v[80:83]
	v_mfma_f32_16x16x32_bf16 v[68:71], v[168:171], v[210:213], v[68:71]
	v_mfma_f32_16x16x32_bf16 v[64:67], v[178:181], v[210:213], v[64:67]
	s_barrier
	s_setprio 0
	s_add_i32 s42, s60, s33
	v_lshl_add_u64 v[214:215], v[214:215], 0, s[18:19]
	s_mov_b32 m0, s42
	ds_read_b128 v[182:185], v150 offset:49152
	ds_read_b128 v[186:189], v150 offset:50176
	ds_read_b128 v[190:193], v150 offset:51200
	ds_read_b128 v[194:197], v150 offset:52224
	ds_read_b128 v[198:201], v150 offset:53248
	ds_read_b128 v[202:205], v150 offset:54272
	ds_read_b128 v[206:209], v150 offset:55296
	ds_read_b128 v[210:213], v150 offset:56320
	global_load_lds_dwordx4 v[214:215], off
	s_add_i32 m0, s42, 0x2000
	s_add_u32 s40, s40, 0x20080
	v_lshl_add_u64 v[214:215], v[216:217], 0, s[18:19]
	s_addc_u32 s41, s41, 0
	s_add_i32 s42, s61, s33
	global_load_lds_dwordx4 v[214:215], off
	v_lshl_add_u64 v[214:215], s[40:41], 0, v[128:129]
	s_mov_b32 m0, s42
	s_nop 0
	global_load_lds_dwordx4 v[214:215], off
	v_lshl_add_u64 v[214:215], s[40:41], 0, v[130:131]
	s_add_i32 m0, s42, 0x2000
	s_nop 0
	global_load_lds_dwordx4 v[214:215], off
	v_lshl_add_u64 v[214:215], v[218:219], 0, s[18:19]
	s_mov_b32 m0, s48
	s_nop 0
	global_load_lds_dwordx4 v[214:215], off
	v_lshl_add_u64 v[214:215], v[220:221], 0, s[18:19]
	s_mov_b32 m0, s49
	s_nop 0
	global_load_lds_dwordx4 v[214:215], off
	s_waitcnt vmcnt(8)
	s_waitcnt lgkmcnt(0)
	s_setprio 1
	s_barrier
	s_waitcnt lgkmcnt(0)
	v_mfma_f32_16x16x32_bf16 v[60:63], v[140:143], v[182:185], v[60:63]
	v_mfma_f32_16x16x32_bf16 v[56:59], v[156:159], v[182:185], v[56:59]
	v_mfma_f32_16x16x32_bf16 v[44:47], v[140:143], v[190:193], v[44:47]
	v_mfma_f32_16x16x32_bf16 v[40:43], v[156:159], v[190:193], v[40:43]
	v_mfma_f32_16x16x32_bf16 v[28:31], v[140:143], v[198:201], v[28:31]
	v_mfma_f32_16x16x32_bf16 v[24:27], v[156:159], v[198:201], v[24:27]
	v_mfma_f32_16x16x32_bf16 v[12:15], v[140:143], v[206:209], v[12:15]
	v_mfma_f32_16x16x32_bf16 v[8:11], v[156:159], v[206:209], v[8:11]
	v_mfma_f32_16x16x32_bf16 v[60:63], v[152:155], v[186:189], v[60:63]
	v_mfma_f32_16x16x32_bf16 v[56:59], v[160:163], v[186:189], v[56:59]
	v_mfma_f32_16x16x32_bf16 v[44:47], v[152:155], v[194:197], v[44:47]
	v_mfma_f32_16x16x32_bf16 v[40:43], v[160:163], v[194:197], v[40:43]
	v_mfma_f32_16x16x32_bf16 v[28:31], v[152:155], v[202:205], v[28:31]
	v_mfma_f32_16x16x32_bf16 v[24:27], v[160:163], v[202:205], v[24:27]
	v_mfma_f32_16x16x32_bf16 v[12:15], v[152:155], v[210:213], v[12:15]
	v_mfma_f32_16x16x32_bf16 v[8:11], v[160:163], v[210:213], v[8:11]
	s_setprio 0
	s_setprio 1
	v_mfma_f32_16x16x32_bf16 v[52:55], v[164:167], v[182:185], v[52:55]
	v_mfma_f32_16x16x32_bf16 v[48:51], v[174:177], v[182:185], v[48:51]
	v_mfma_f32_16x16x32_bf16 v[36:39], v[164:167], v[190:193], v[36:39]
	v_mfma_f32_16x16x32_bf16 v[32:35], v[174:177], v[190:193], v[32:35]
	v_mfma_f32_16x16x32_bf16 v[20:23], v[164:167], v[198:201], v[20:23]
	v_mfma_f32_16x16x32_bf16 v[16:19], v[174:177], v[198:201], v[16:19]
	v_mfma_f32_16x16x32_bf16 v[4:7], v[164:167], v[206:209], v[4:7]
	v_mfma_f32_16x16x32_bf16 v[0:3], v[174:177], v[206:209], v[0:3]
	v_mfma_f32_16x16x32_bf16 v[52:55], v[168:171], v[186:189], v[52:55]
	v_mfma_f32_16x16x32_bf16 v[48:51], v[178:181], v[186:189], v[48:51]
	v_mfma_f32_16x16x32_bf16 v[36:39], v[168:171], v[194:197], v[36:39]
	v_mfma_f32_16x16x32_bf16 v[32:35], v[178:181], v[194:197], v[32:35]
	v_mfma_f32_16x16x32_bf16 v[20:23], v[168:171], v[202:205], v[20:23]
	v_mfma_f32_16x16x32_bf16 v[16:19], v[178:181], v[202:205], v[16:19]
	v_mfma_f32_16x16x32_bf16 v[4:7], v[168:171], v[210:213], v[4:7]
	v_mfma_f32_16x16x32_bf16 v[0:3], v[178:181], v[210:213], v[0:3]
	s_barrier
	s_setprio 0
	s_add_i32 s59, s59, 2
	s_add_u32 s38, s38, 0x100
	s_addc_u32 s39, s39, 0
	s_add_u32 s57, s57, 0x100
	s_addc_u32 s58, s58, 0
	s_cmp_gt_u32 s59, 5
	s_cbranch_scc0 .LBB0_976
	s_and_b64 vcc, exec, s[20:21]
	s_cbranch_vccz .LBB0_979
	s_barrier

.LBB0_1086:
	ds_read_b128 v[140:143], v176
	ds_read_b128 v[144:147], v176 offset:1024
	ds_read_b128 v[148:151], v176 offset:2048
	ds_read_b128 v[152:155], v176 offset:3072
	ds_read_b128 v[156:159], v177
	ds_read_b128 v[160:163], v177 offset:1024
	ds_read_b128 v[164:167], v177 offset:2048
	ds_read_b128 v[168:171], v177 offset:3072
	s_add_u32 s58, s8, 0xfff80080
	s_addc_u32 s59, s9, -1
	s_cmp_eq_u32 s63, 28
	s_cselect_b32 s61, s1, s59
	s_cselect_b32 s60, s25, s58
	s_cselect_b32 s59, s49, s62
	s_cselect_b32 s58, s51, s57
	v_lshl_add_u64 v[214:215], s[8:9], 0, v[132:133]
	s_add_i32 m0, s66, 0xc000
	ds_read_b128 v[182:185], v178
	ds_read_b128 v[186:189], v178 offset:1024
	ds_read_b128 v[190:193], v178 offset:2048
	ds_read_b128 v[194:197], v178 offset:3072
	ds_read_b128 v[198:201], v178 offset:4096
	ds_read_b128 v[202:205], v178 offset:5120
	ds_read_b128 v[206:209], v178 offset:6144
	ds_read_b128 v[210:213], v178 offset:7168
	global_load_lds_dwordx4 v[214:215], off
	v_lshl_add_u64 v[214:215], s[8:9], 0, v[134:135]
	s_add_i32 m0, s66, 0xe000
	s_nop 0
	global_load_lds_dwordx4 v[214:215], off
	s_waitcnt vmcnt(8)
	s_waitcnt lgkmcnt(0)
	s_setprio 1
	s_barrier
	s_waitcnt lgkmcnt(0)
	v_mfma_f32_16x16x32_bf16 v[60:63], v[182:185], v[140:143], v[60:63]
	v_mfma_f32_16x16x32_bf16 v[56:59], v[182:185], v[148:151], v[56:59]
	v_mfma_f32_16x16x32_bf16 v[44:47], v[190:193], v[140:143], v[44:47]
	v_mfma_f32_16x16x32_bf16 v[40:43], v[190:193], v[148:151], v[40:43]
	v_mfma_f32_16x16x32_bf16 v[28:31], v[198:201], v[140:143], v[28:31]
	v_mfma_f32_16x16x32_bf16 v[24:27], v[198:201], v[148:151], v[24:27]
	v_mfma_f32_16x16x32_bf16 v[12:15], v[206:209], v[140:143], v[12:15]
	v_mfma_f32_16x16x32_bf16 v[8:11], v[206:209], v[148:151], v[8:11]
	v_mfma_f32_16x16x32_bf16 v[60:63], v[186:189], v[144:147], v[60:63]
	v_mfma_f32_16x16x32_bf16 v[56:59], v[186:189], v[152:155], v[56:59]
	v_mfma_f32_16x16x32_bf16 v[44:47], v[194:197], v[144:147], v[44:47]
	v_mfma_f32_16x16x32_bf16 v[40:43], v[194:197], v[152:155], v[40:43]
	v_mfma_f32_16x16x32_bf16 v[28:31], v[202:205], v[144:147], v[28:31]
	v_mfma_f32_16x16x32_bf16 v[24:27], v[202:205], v[152:155], v[24:27]
	v_mfma_f32_16x16x32_bf16 v[12:15], v[210:213], v[144:147], v[12:15]
	v_mfma_f32_16x16x32_bf16 v[8:11], v[210:213], v[152:155], v[8:11]
	s_setprio 0
	s_setprio 1
	v_mfma_f32_16x16x32_bf16 v[52:55], v[182:185], v[156:159], v[52:55]
	v_mfma_f32_16x16x32_bf16 v[48:51], v[182:185], v[164:167], v[48:51]
	v_mfma_f32_16x16x32_bf16 v[36:39], v[190:193], v[156:159], v[36:39]
	v_mfma_f32_16x16x32_bf16 v[32:35], v[190:193], v[164:167], v[32:35]
	v_mfma_f32_16x16x32_bf16 v[20:23], v[198:201], v[156:159], v[20:23]
	v_mfma_f32_16x16x32_bf16 v[16:19], v[198:201], v[164:167], v[16:19]
	v_mfma_f32_16x16x32_bf16 v[4:7], v[206:209], v[156:159], v[4:7]
	v_mfma_f32_16x16x32_bf16 v[0:3], v[206:209], v[164:167], v[0:3]
	v_mfma_f32_16x16x32_bf16 v[52:55], v[186:189], v[160:163], v[52:55]
	v_mfma_f32_16x16x32_bf16 v[48:51], v[186:189], v[168:171], v[48:51]
	v_mfma_f32_16x16x32_bf16 v[36:39], v[194:197], v[160:163], v[36:39]
	v_mfma_f32_16x16x32_bf16 v[32:35], v[194:197], v[168:171], v[32:35]
	v_mfma_f32_16x16x32_bf16 v[20:23], v[202:205], v[160:163], v[20:23]
	v_mfma_f32_16x16x32_bf16 v[16:19], v[202:205], v[168:171], v[16:19]
	v_mfma_f32_16x16x32_bf16 v[4:7], v[210:213], v[160:163], v[4:7]
	v_mfma_f32_16x16x32_bf16 v[0:3], v[210:213], v[168:171], v[0:3]
	s_barrier
	s_setprio 0
	s_add_i32 vcc_lo, s89, s65
	v_lshl_add_u64 v[214:215], s[58:59], 0, v[128:129]
	s_mov_b32 m0, vcc_lo
	ds_read_b128 v[182:185], v178 offset:16384
	ds_read_b128 v[186:189], v178 offset:17408
	ds_read_b128 v[190:193], v178 offset:18432
	ds_read_b128 v[194:197], v178 offset:19456
	ds_read_b128 v[198:201], v178 offset:20480
	ds_read_b128 v[202:205], v178 offset:21504
	ds_read_b128 v[206:209], v178 offset:22528
	ds_read_b128 v[210:213], v178 offset:23552
	global_load_lds_dwordx4 v[214:215], off
	s_add_i32 m0, vcc_lo, 0x2000
	s_add_u32 vcc_lo, s58, 0x80000
	v_lshl_add_u64 v[216:217], s[58:59], 0, v[130:131]
	s_addc_u32 vcc_hi, s59, 0
	s_add_i32 s2, s90, s65
	global_load_lds_dwordx4 v[216:217], off
	v_lshl_add_u64 v[218:219], vcc, 0, v[128:129]
	s_mov_b32 m0, s2
	v_lshl_add_u64 v[220:221], s[60:61], 0, v[130:131]
	global_load_lds_dwordx4 v[218:219], off
	v_lshl_add_u64 v[218:219], vcc, 0, v[130:131]
	s_add_i32 m0, s2, 0x2000
	s_nop 0
	global_load_lds_dwordx4 v[218:219], off
	v_lshl_add_u64 v[218:219], s[60:61], 0, v[128:129]
	s_mov_b32 m0, s66
	s_nop 0
	global_load_lds_dwordx4 v[218:219], off
	s_mov_b32 m0, s67
	s_nop 0
	global_load_lds_dwordx4 v[220:221], off
	s_waitcnt vmcnt(8)
	s_waitcnt lgkmcnt(0)
	s_setprio 1
	s_barrier
	s_waitcnt lgkmcnt(0)
	v_mfma_f32_16x16x32_bf16 v[124:127], v[182:185], v[140:143], v[124:127]
	v_mfma_f32_16x16x32_bf16 v[116:119], v[182:185], v[148:151], v[116:119]
	v_mfma_f32_16x16x32_bf16 v[108:111], v[190:193], v[140:143], v[108:111]
	v_mfma_f32_16x16x32_bf16 v[100:103], v[190:193], v[148:151], v[100:103]
	v_mfma_f32_16x16x32_bf16 v[92:95], v[198:201], v[140:143], v[92:95]
	v_mfma_f32_16x16x32_bf16 v[84:87], v[198:201], v[148:151], v[84:87]
	v_mfma_f32_16x16x32_bf16 v[76:79], v[206:209], v[140:143], v[76:79]
	v_mfma_f32_16x16x32_bf16 v[68:71], v[206:209], v[148:151], v[68:71]
	v_mfma_f32_16x16x32_bf16 v[124:127], v[186:189], v[144:147], v[124:127]
	v_mfma_f32_16x16x32_bf16 v[116:119], v[186:189], v[152:155], v[116:119]
	v_mfma_f32_16x16x32_bf16 v[108:111], v[194:197], v[144:147], v[108:111]
	v_mfma_f32_16x16x32_bf16 v[100:103], v[194:197], v[152:155], v[100:103]
	v_mfma_f32_16x16x32_bf16 v[92:95], v[202:205], v[144:147], v[92:95]
	v_mfma_f32_16x16x32_bf16 v[84:87], v[202:205], v[152:155], v[84:87]
	v_mfma_f32_16x16x32_bf16 v[76:79], v[210:213], v[144:147], v[76:79]
	v_mfma_f32_16x16x32_bf16 v[68:71], v[210:213], v[152:155], v[68:71]
	s_setprio 0
	s_setprio 1
	v_mfma_f32_16x16x32_bf16 v[120:123], v[182:185], v[156:159], v[120:123]
	v_mfma_f32_16x16x32_bf16 v[112:115], v[182:185], v[164:167], v[112:115]
	v_mfma_f32_16x16x32_bf16 v[104:107], v[190:193], v[156:159], v[104:107]
	v_mfma_f32_16x16x32_bf16 v[96:99], v[190:193], v[164:167], v[96:99]
	v_mfma_f32_16x16x32_bf16 v[88:91], v[198:201], v[156:159], v[88:91]
	v_mfma_f32_16x16x32_bf16 v[80:83], v[198:201], v[164:167], v[80:83]
	v_mfma_f32_16x16x32_bf16 v[72:75], v[206:209], v[156:159], v[72:75]
	v_mfma_f32_16x16x32_bf16 v[64:67], v[206:209], v[164:167], v[64:67]
	v_mfma_f32_16x16x32_bf16 v[120:123], v[186:189], v[160:163], v[120:123]
	v_mfma_f32_16x16x32_bf16 v[112:115], v[186:189], v[168:171], v[112:115]
	v_mfma_f32_16x16x32_bf16 v[104:107], v[194:197], v[160:163], v[104:107]
	v_mfma_f32_16x16x32_bf16 v[96:99], v[194:197], v[168:171], v[96:99]
	v_mfma_f32_16x16x32_bf16 v[88:91], v[202:205], v[160:163], v[88:91]
	v_mfma_f32_16x16x32_bf16 v[80:83], v[202:205], v[168:171], v[80:83]
	v_mfma_f32_16x16x32_bf16 v[72:75], v[210:213], v[160:163], v[72:75]
	v_mfma_f32_16x16x32_bf16 v[64:67], v[210:213], v[168:171], v[64:67]
	s_barrier
	s_setprio 0
	s_add_i32 s2, 0, 0x18000
	s_add_i32 s3, 0, 0x1c000
	v_add_u32_e32 v152, s2, v175
	v_add_u32_e32 v168, s3, v175
	ds_read_b128 v[140:143], v152
	ds_read_b128 v[144:147], v152 offset:1024
	ds_read_b128 v[148:151], v152 offset:2048
	ds_read_b128 v[152:155], v152 offset:3072
	ds_read_b128 v[156:159], v168
	ds_read_b128 v[160:163], v168 offset:1024
	ds_read_b128 v[164:167], v168 offset:2048
	ds_read_b128 v[168:171], v168 offset:3072
	s_add_u32 s60, s60, 0x80000
	s_addc_u32 s61, s61, 0
	s_mov_b32 m0, s68
	v_lshl_add_u64 v[222:223], s[60:61], 0, v[128:129]
	ds_read_b128 v[182:185], v178 offset:32768
	ds_read_b128 v[186:189], v178 offset:33792
	ds_read_b128 v[190:193], v178 offset:34816
	ds_read_b128 v[194:197], v178 offset:35840
	ds_read_b128 v[198:201], v178 offset:36864
	ds_read_b128 v[202:205], v178 offset:37888
	ds_read_b128 v[206:209], v178 offset:38912
	ds_read_b128 v[210:213], v178 offset:39936
	global_load_lds_dwordx4 v[222:223], off
	v_lshl_add_u64 v[222:223], s[60:61], 0, v[130:131]
	s_mov_b32 m0, s69
	s_nop 0
	global_load_lds_dwordx4 v[222:223], off
	s_waitcnt vmcnt(8)
	s_waitcnt lgkmcnt(0)
	s_setprio 1
	s_barrier
	s_waitcnt lgkmcnt(0)
	v_mfma_f32_16x16x32_bf16 v[60:63], v[182:185], v[140:143], v[60:63]
	v_mfma_f32_16x16x32_bf16 v[56:59], v[182:185], v[148:151], v[56:59]
	v_mfma_f32_16x16x32_bf16 v[44:47], v[190:193], v[140:143], v[44:47]
	v_mfma_f32_16x16x32_bf16 v[40:43], v[190:193], v[148:151], v[40:43]
	v_mfma_f32_16x16x32_bf16 v[28:31], v[198:201], v[140:143], v[28:31]
	v_mfma_f32_16x16x32_bf16 v[24:27], v[198:201], v[148:151], v[24:27]
	v_mfma_f32_16x16x32_bf16 v[12:15], v[206:209], v[140:143], v[12:15]
	v_mfma_f32_16x16x32_bf16 v[8:11], v[206:209], v[148:151], v[8:11]
	v_mfma_f32_16x16x32_bf16 v[60:63], v[186:189], v[144:147], v[60:63]
	v_mfma_f32_16x16x32_bf16 v[56:59], v[186:189], v[152:155], v[56:59]
	v_mfma_f32_16x16x32_bf16 v[44:47], v[194:197], v[144:147], v[44:47]
	v_mfma_f32_16x16x32_bf16 v[40:43], v[194:197], v[152:155], v[40:43]
	v_mfma_f32_16x16x32_bf16 v[28:31], v[202:205], v[144:147], v[28:31]
	v_mfma_f32_16x16x32_bf16 v[24:27], v[202:205], v[152:155], v[24:27]
	v_mfma_f32_16x16x32_bf16 v[12:15], v[210:213], v[144:147], v[12:15]
	v_mfma_f32_16x16x32_bf16 v[8:11], v[210:213], v[152:155], v[8:11]
	s_setprio 0
	s_setprio 1
	v_mfma_f32_16x16x32_bf16 v[52:55], v[182:185], v[156:159], v[52:55]
	v_mfma_f32_16x16x32_bf16 v[48:51], v[182:185], v[164:167], v[48:51]
	v_mfma_f32_16x16x32_bf16 v[36:39], v[190:193], v[156:159], v[36:39]
	v_mfma_f32_16x16x32_bf16 v[32:35], v[190:193], v[164:167], v[32:35]
	v_mfma_f32_16x16x32_bf16 v[20:23], v[198:201], v[156:159], v[20:23]
	v_mfma_f32_16x16x32_bf16 v[16:19], v[198:201], v[164:167], v[16:19]
	v_mfma_f32_16x16x32_bf16 v[4:7], v[206:209], v[156:159], v[4:7]
	v_mfma_f32_16x16x32_bf16 v[0:3], v[206:209], v[164:167], v[0:3]
	v_mfma_f32_16x16x32_bf16 v[52:55], v[186:189], v[160:163], v[52:55]
	v_mfma_f32_16x16x32_bf16 v[48:51], v[186:189], v[168:171], v[48:51]
	v_mfma_f32_16x16x32_bf16 v[36:39], v[194:197], v[160:163], v[36:39]
	v_mfma_f32_16x16x32_bf16 v[32:35], v[194:197], v[168:171], v[32:35]
	v_mfma_f32_16x16x32_bf16 v[20:23], v[202:205], v[160:163], v[20:23]
	v_mfma_f32_16x16x32_bf16 v[16:19], v[202:205], v[168:171], v[16:19]
	v_mfma_f32_16x16x32_bf16 v[4:7], v[210:213], v[160:163], v[4:7]
	v_mfma_f32_16x16x32_bf16 v[0:3], v[210:213], v[168:171], v[0:3]
	s_barrier
	s_setprio 0
	s_add_i32 s2, s2, s65
	v_lshl_add_u64 v[214:215], v[214:215], 0, s[20:21]
	s_mov_b32 m0, s2
	ds_read_b128 v[182:185], v178 offset:49152
	ds_read_b128 v[186:189], v178 offset:50176
	ds_read_b128 v[190:193], v178 offset:51200
	ds_read_b128 v[194:197], v178 offset:52224
	ds_read_b128 v[198:201], v178 offset:53248
	ds_read_b128 v[202:205], v178 offset:54272
	ds_read_b128 v[206:209], v178 offset:55296
	ds_read_b128 v[210:213], v178 offset:56320
	global_load_lds_dwordx4 v[214:215], off
	s_add_i32 m0, s2, 0x2000
	s_add_u32 s58, s58, 0x80080
	v_lshl_add_u64 v[214:215], v[216:217], 0, s[20:21]
	s_addc_u32 s59, s59, 0
	s_add_i32 s2, s3, s65
	global_load_lds_dwordx4 v[214:215], off
	v_lshl_add_u64 v[214:215], s[58:59], 0, v[128:129]
	s_mov_b32 m0, s2
	s_nop 0
	global_load_lds_dwordx4 v[214:215], off
	v_lshl_add_u64 v[214:215], s[58:59], 0, v[130:131]
	s_add_i32 m0, s2, 0x2000
	s_nop 0
	global_load_lds_dwordx4 v[214:215], off
	v_lshl_add_u64 v[214:215], v[218:219], 0, s[20:21]
	s_mov_b32 m0, s80
	s_nop 0
	global_load_lds_dwordx4 v[214:215], off
	v_lshl_add_u64 v[214:215], v[220:221], 0, s[20:21]
	s_mov_b32 m0, s81
	s_nop 0
	global_load_lds_dwordx4 v[214:215], off
	s_waitcnt vmcnt(8)
	s_waitcnt lgkmcnt(0)
	s_setprio 1
	s_barrier
	s_waitcnt lgkmcnt(0)
	v_mfma_f32_16x16x32_bf16 v[124:127], v[182:185], v[140:143], v[124:127]
	v_mfma_f32_16x16x32_bf16 v[116:119], v[182:185], v[148:151], v[116:119]
	v_mfma_f32_16x16x32_bf16 v[108:111], v[190:193], v[140:143], v[108:111]
	v_mfma_f32_16x16x32_bf16 v[100:103], v[190:193], v[148:151], v[100:103]
	v_mfma_f32_16x16x32_bf16 v[92:95], v[198:201], v[140:143], v[92:95]
	v_mfma_f32_16x16x32_bf16 v[84:87], v[198:201], v[148:151], v[84:87]
	v_mfma_f32_16x16x32_bf16 v[76:79], v[206:209], v[140:143], v[76:79]
	v_mfma_f32_16x16x32_bf16 v[68:71], v[206:209], v[148:151], v[68:71]
	v_mfma_f32_16x16x32_bf16 v[124:127], v[186:189], v[144:147], v[124:127]
	v_mfma_f32_16x16x32_bf16 v[116:119], v[186:189], v[152:155], v[116:119]
	v_mfma_f32_16x16x32_bf16 v[108:111], v[194:197], v[144:147], v[108:111]
	v_mfma_f32_16x16x32_bf16 v[100:103], v[194:197], v[152:155], v[100:103]
	v_mfma_f32_16x16x32_bf16 v[92:95], v[202:205], v[144:147], v[92:95]
	v_mfma_f32_16x16x32_bf16 v[84:87], v[202:205], v[152:155], v[84:87]
	v_mfma_f32_16x16x32_bf16 v[76:79], v[210:213], v[144:147], v[76:79]
	v_mfma_f32_16x16x32_bf16 v[68:71], v[210:213], v[152:155], v[68:71]
	s_setprio 0
	s_setprio 1
	v_mfma_f32_16x16x32_bf16 v[120:123], v[182:185], v[156:159], v[120:123]
	v_mfma_f32_16x16x32_bf16 v[112:115], v[182:185], v[164:167], v[112:115]
	v_mfma_f32_16x16x32_bf16 v[104:107], v[190:193], v[156:159], v[104:107]
	v_mfma_f32_16x16x32_bf16 v[96:99], v[190:193], v[164:167], v[96:99]
	v_mfma_f32_16x16x32_bf16 v[88:91], v[198:201], v[156:159], v[88:91]
	v_mfma_f32_16x16x32_bf16 v[80:83], v[198:201], v[164:167], v[80:83]
	v_mfma_f32_16x16x32_bf16 v[72:75], v[206:209], v[156:159], v[72:75]
	v_mfma_f32_16x16x32_bf16 v[64:67], v[206:209], v[164:167], v[64:67]
	v_mfma_f32_16x16x32_bf16 v[120:123], v[186:189], v[160:163], v[120:123]
	v_mfma_f32_16x16x32_bf16 v[112:115], v[186:189], v[168:171], v[112:115]
	v_mfma_f32_16x16x32_bf16 v[104:107], v[194:197], v[160:163], v[104:107]
	v_mfma_f32_16x16x32_bf16 v[96:99], v[194:197], v[168:171], v[96:99]
	v_mfma_f32_16x16x32_bf16 v[88:91], v[202:205], v[160:163], v[88:91]
	v_mfma_f32_16x16x32_bf16 v[80:83], v[202:205], v[168:171], v[80:83]
	v_mfma_f32_16x16x32_bf16 v[72:75], v[210:213], v[160:163], v[72:75]
	v_mfma_f32_16x16x32_bf16 v[64:67], v[210:213], v[168:171], v[64:67]
	s_barrier
	s_setprio 0
	s_add_i32 s63, s63, 2
	s_add_u32 s8, s8, 0x100
	s_addc_u32 s9, s9, 0
	s_add_u32 s57, s57, 0x100
	s_addc_u32 s62, s62, 0
	s_cmp_gt_u32 s63, 29
	s_cbranch_scc0 .LBB0_1086
	s_and_b64 vcc, exec, s[22:23]
	s_cbranch_vccz .LBB0_1089
	s_barrier

.LBB0_1294:
	ds_read_b128 v[142:145], v151
	ds_read_b128 v[154:157], v151 offset:1024
	ds_read_b128 v[158:161], v151 offset:2048
	ds_read_b128 v[162:165], v151 offset:3072
	ds_read_b128 v[166:169], v152
	ds_read_b128 v[174:177], v152 offset:1024
	ds_read_b128 v[178:181], v152 offset:2048
	ds_read_b128 v[182:185], v152 offset:3072
	s_add_u32 s22, s2, 0xffea0080
	s_addc_u32 s23, s3, -1
	s_cmpk_eq_i32 s49, 0x54
	s_cselect_b32 s25, s19, s23
	s_cselect_b32 s24, s18, s22
	s_cselect_b32 s23, s21, s48
	s_cselect_b32 s22, s20, s47
	v_lshl_add_u64 v[146:147], s[2:3], 0, v[134:135]
	s_add_i32 m0, s29, 0xc000
	ds_read_b128 v[186:189], v153
	ds_read_b128 v[190:193], v153 offset:1024
	ds_read_b128 v[194:197], v153 offset:2048
	ds_read_b128 v[198:201], v153 offset:3072
	ds_read_b128 v[202:205], v153 offset:4096
	ds_read_b128 v[206:209], v153 offset:5120
	ds_read_b128 v[210:213], v153 offset:6144
	ds_read_b128 v[214:217], v153 offset:7168
	global_load_lds_dwordx4 v[146:147], off
	v_lshl_add_u64 v[146:147], s[2:3], 0, v[136:137]
	s_add_i32 m0, s29, 0xe000
	s_nop 0
	global_load_lds_dwordx4 v[146:147], off
	s_waitcnt vmcnt(8)
	s_waitcnt lgkmcnt(0)
	s_setprio 1
	s_barrier
	s_waitcnt lgkmcnt(0)
	v_mfma_f32_16x16x32_bf16 v[124:127], v[142:145], v[186:189], v[124:127]
	v_mfma_f32_16x16x32_bf16 v[120:123], v[158:161], v[186:189], v[120:123]
	v_mfma_f32_16x16x32_bf16 v[108:111], v[142:145], v[194:197], v[108:111]
	v_mfma_f32_16x16x32_bf16 v[104:107], v[158:161], v[194:197], v[104:107]
	v_mfma_f32_16x16x32_bf16 v[92:95], v[142:145], v[202:205], v[92:95]
	v_mfma_f32_16x16x32_bf16 v[88:91], v[158:161], v[202:205], v[88:91]
	v_mfma_f32_16x16x32_bf16 v[76:79], v[142:145], v[210:213], v[76:79]
	v_mfma_f32_16x16x32_bf16 v[72:75], v[158:161], v[210:213], v[72:75]
	v_mfma_f32_16x16x32_bf16 v[124:127], v[154:157], v[190:193], v[124:127]
	v_mfma_f32_16x16x32_bf16 v[120:123], v[162:165], v[190:193], v[120:123]
	v_mfma_f32_16x16x32_bf16 v[108:111], v[154:157], v[198:201], v[108:111]
	v_mfma_f32_16x16x32_bf16 v[104:107], v[162:165], v[198:201], v[104:107]
	v_mfma_f32_16x16x32_bf16 v[92:95], v[154:157], v[206:209], v[92:95]
	v_mfma_f32_16x16x32_bf16 v[88:91], v[162:165], v[206:209], v[88:91]
	v_mfma_f32_16x16x32_bf16 v[76:79], v[154:157], v[214:217], v[76:79]
	v_mfma_f32_16x16x32_bf16 v[72:75], v[162:165], v[214:217], v[72:75]
	s_setprio 0
	s_setprio 1
	v_mfma_f32_16x16x32_bf16 v[116:119], v[166:169], v[186:189], v[116:119]
	v_mfma_f32_16x16x32_bf16 v[112:115], v[178:181], v[186:189], v[112:115]
	v_mfma_f32_16x16x32_bf16 v[100:103], v[166:169], v[194:197], v[100:103]
	v_mfma_f32_16x16x32_bf16 v[96:99], v[178:181], v[194:197], v[96:99]
	v_mfma_f32_16x16x32_bf16 v[84:87], v[166:169], v[202:205], v[84:87]
	v_mfma_f32_16x16x32_bf16 v[80:83], v[178:181], v[202:205], v[80:83]
	v_mfma_f32_16x16x32_bf16 v[68:71], v[166:169], v[210:213], v[68:71]
	v_mfma_f32_16x16x32_bf16 v[64:67], v[178:181], v[210:213], v[64:67]
	v_mfma_f32_16x16x32_bf16 v[116:119], v[174:177], v[190:193], v[116:119]
	v_mfma_f32_16x16x32_bf16 v[112:115], v[182:185], v[190:193], v[112:115]
	v_mfma_f32_16x16x32_bf16 v[100:103], v[174:177], v[198:201], v[100:103]
	v_mfma_f32_16x16x32_bf16 v[96:99], v[182:185], v[198:201], v[96:99]
	v_mfma_f32_16x16x32_bf16 v[84:87], v[174:177], v[206:209], v[84:87]
	v_mfma_f32_16x16x32_bf16 v[80:83], v[182:185], v[206:209], v[80:83]
	v_mfma_f32_16x16x32_bf16 v[68:71], v[174:177], v[214:217], v[68:71]
	v_mfma_f32_16x16x32_bf16 v[64:67], v[182:185], v[214:217], v[64:67]
	s_barrier
	s_setprio 0
	s_add_i32 s50, s39, s28
	v_lshl_add_u64 v[146:147], s[22:23], 0, v[128:129]
	s_mov_b32 m0, s50
	ds_read_b128 v[186:189], v153 offset:16384
	ds_read_b128 v[190:193], v153 offset:17408
	ds_read_b128 v[194:197], v153 offset:18432
	ds_read_b128 v[198:201], v153 offset:19456
	ds_read_b128 v[202:205], v153 offset:20480
	ds_read_b128 v[206:209], v153 offset:21504
	ds_read_b128 v[210:213], v153 offset:22528
	ds_read_b128 v[214:217], v153 offset:23552
	global_load_lds_dwordx4 v[146:147], off
	s_add_i32 m0, s50, 0x2000
	s_add_u32 s50, s22, 0x160000
	v_lshl_add_u64 v[170:171], s[22:23], 0, v[130:131]
	s_addc_u32 s51, s23, 0
	s_add_i32 s52, s40, s28
	global_load_lds_dwordx4 v[170:171], off
	v_lshl_add_u64 v[218:219], s[50:51], 0, v[128:129]
	s_mov_b32 m0, s52
	v_lshl_add_u64 v[220:221], s[24:25], 0, v[130:131]
	global_load_lds_dwordx4 v[218:219], off
	v_lshl_add_u64 v[218:219], s[50:51], 0, v[130:131]
	s_add_i32 m0, s52, 0x2000
	s_nop 0
	global_load_lds_dwordx4 v[218:219], off
	v_lshl_add_u64 v[218:219], s[24:25], 0, v[128:129]
	s_mov_b32 m0, s29
	s_nop 0
	global_load_lds_dwordx4 v[218:219], off
	s_mov_b32 m0, s30
	s_nop 0
	global_load_lds_dwordx4 v[220:221], off
	s_waitcnt vmcnt(8)
	s_waitcnt lgkmcnt(0)
	s_setprio 1
	s_barrier
	s_waitcnt lgkmcnt(0)
	v_mfma_f32_16x16x32_bf16 v[60:63], v[142:145], v[186:189], v[60:63]
	v_mfma_f32_16x16x32_bf16 v[56:59], v[158:161], v[186:189], v[56:59]
	v_mfma_f32_16x16x32_bf16 v[44:47], v[142:145], v[194:197], v[44:47]
	v_mfma_f32_16x16x32_bf16 v[40:43], v[158:161], v[194:197], v[40:43]
	v_mfma_f32_16x16x32_bf16 v[28:31], v[142:145], v[202:205], v[28:31]
	v_mfma_f32_16x16x32_bf16 v[24:27], v[158:161], v[202:205], v[24:27]
	v_mfma_f32_16x16x32_bf16 v[12:15], v[142:145], v[210:213], v[12:15]
	v_mfma_f32_16x16x32_bf16 v[8:11], v[158:161], v[210:213], v[8:11]
	v_mfma_f32_16x16x32_bf16 v[60:63], v[154:157], v[190:193], v[60:63]
	v_mfma_f32_16x16x32_bf16 v[56:59], v[162:165], v[190:193], v[56:59]
	v_mfma_f32_16x16x32_bf16 v[44:47], v[154:157], v[198:201], v[44:47]
	v_mfma_f32_16x16x32_bf16 v[40:43], v[162:165], v[198:201], v[40:43]
	v_mfma_f32_16x16x32_bf16 v[28:31], v[154:157], v[206:209], v[28:31]
	v_mfma_f32_16x16x32_bf16 v[24:27], v[162:165], v[206:209], v[24:27]
	v_mfma_f32_16x16x32_bf16 v[12:15], v[154:157], v[214:217], v[12:15]
	v_mfma_f32_16x16x32_bf16 v[8:11], v[162:165], v[214:217], v[8:11]
	s_setprio 0
	s_setprio 1
	v_mfma_f32_16x16x32_bf16 v[52:55], v[166:169], v[186:189], v[52:55]
	v_mfma_f32_16x16x32_bf16 v[48:51], v[178:181], v[186:189], v[48:51]
	v_mfma_f32_16x16x32_bf16 v[36:39], v[166:169], v[194:197], v[36:39]
	v_mfma_f32_16x16x32_bf16 v[32:35], v[178:181], v[194:197], v[32:35]
	v_mfma_f32_16x16x32_bf16 v[20:23], v[166:169], v[202:205], v[20:23]
	v_mfma_f32_16x16x32_bf16 v[16:19], v[178:181], v[202:205], v[16:19]
	v_mfma_f32_16x16x32_bf16 v[4:7], v[166:169], v[210:213], v[4:7]
	v_mfma_f32_16x16x32_bf16 v[0:3], v[178:181], v[210:213], v[0:3]
	v_mfma_f32_16x16x32_bf16 v[52:55], v[174:177], v[190:193], v[52:55]
	v_mfma_f32_16x16x32_bf16 v[48:51], v[182:185], v[190:193], v[48:51]
	v_mfma_f32_16x16x32_bf16 v[36:39], v[174:177], v[198:201], v[36:39]
	v_mfma_f32_16x16x32_bf16 v[32:35], v[182:185], v[198:201], v[32:35]
	v_mfma_f32_16x16x32_bf16 v[20:23], v[174:177], v[206:209], v[20:23]
	v_mfma_f32_16x16x32_bf16 v[16:19], v[182:185], v[206:209], v[16:19]
	v_mfma_f32_16x16x32_bf16 v[4:7], v[174:177], v[214:217], v[4:7]
	v_mfma_f32_16x16x32_bf16 v[0:3], v[182:185], v[214:217], v[0:3]
	s_barrier
	s_setprio 0
	s_add_i32 s50, 0, 0x18000
	v_add_u32_e32 v132, s50, v149
	s_add_i32 s51, 0, 0x1c000
	ds_read_b128 v[142:145], v132
	ds_read_b128 v[154:157], v132 offset:1024
	ds_read_b128 v[158:161], v132 offset:2048
	ds_read_b128 v[162:165], v132 offset:3072
	v_add_u32_e32 v132, s51, v149
	ds_read_b128 v[166:169], v132
	ds_read_b128 v[174:177], v132 offset:1024
	ds_read_b128 v[178:181], v132 offset:2048
	ds_read_b128 v[182:185], v132 offset:3072
	s_add_u32 s24, s24, 0x160000
	s_addc_u32 s25, s25, 0
	s_mov_b32 m0, s31
	v_lshl_add_u64 v[222:223], s[24:25], 0, v[128:129]
	ds_read_b128 v[186:189], v153 offset:32768
	ds_read_b128 v[190:193], v153 offset:33792
	ds_read_b128 v[194:197], v153 offset:34816
	ds_read_b128 v[198:201], v153 offset:35840
	ds_read_b128 v[202:205], v153 offset:36864
	ds_read_b128 v[206:209], v153 offset:37888
	ds_read_b128 v[210:213], v153 offset:38912
	ds_read_b128 v[214:217], v153 offset:39936
	global_load_lds_dwordx4 v[222:223], off
	v_lshl_add_u64 v[222:223], s[24:25], 0, v[130:131]
	s_mov_b32 m0, s33
	s_nop 0
	global_load_lds_dwordx4 v[222:223], off
	s_waitcnt vmcnt(8)
	s_waitcnt lgkmcnt(0)
	s_setprio 1
	s_barrier
	s_waitcnt lgkmcnt(0)
	v_mfma_f32_16x16x32_bf16 v[124:127], v[142:145], v[186:189], v[124:127]
	v_mfma_f32_16x16x32_bf16 v[120:123], v[158:161], v[186:189], v[120:123]
	v_mfma_f32_16x16x32_bf16 v[108:111], v[142:145], v[194:197], v[108:111]
	v_mfma_f32_16x16x32_bf16 v[104:107], v[158:161], v[194:197], v[104:107]
	v_mfma_f32_16x16x32_bf16 v[92:95], v[142:145], v[202:205], v[92:95]
	v_mfma_f32_16x16x32_bf16 v[88:91], v[158:161], v[202:205], v[88:91]
	v_mfma_f32_16x16x32_bf16 v[76:79], v[142:145], v[210:213], v[76:79]
	v_mfma_f32_16x16x32_bf16 v[72:75], v[158:161], v[210:213], v[72:75]
	v_mfma_f32_16x16x32_bf16 v[124:127], v[154:157], v[190:193], v[124:127]
	v_mfma_f32_16x16x32_bf16 v[120:123], v[162:165], v[190:193], v[120:123]
	v_mfma_f32_16x16x32_bf16 v[108:111], v[154:157], v[198:201], v[108:111]
	v_mfma_f32_16x16x32_bf16 v[104:107], v[162:165], v[198:201], v[104:107]
	v_mfma_f32_16x16x32_bf16 v[92:95], v[154:157], v[206:209], v[92:95]
	v_mfma_f32_16x16x32_bf16 v[88:91], v[162:165], v[206:209], v[88:91]
	v_mfma_f32_16x16x32_bf16 v[76:79], v[154:157], v[214:217], v[76:79]
	v_mfma_f32_16x16x32_bf16 v[72:75], v[162:165], v[214:217], v[72:75]
	s_setprio 0
	s_setprio 1
	v_mfma_f32_16x16x32_bf16 v[116:119], v[166:169], v[186:189], v[116:119]
	v_mfma_f32_16x16x32_bf16 v[112:115], v[178:181], v[186:189], v[112:115]
	v_mfma_f32_16x16x32_bf16 v[100:103], v[166:169], v[194:197], v[100:103]
	v_mfma_f32_16x16x32_bf16 v[96:99], v[178:181], v[194:197], v[96:99]
	v_mfma_f32_16x16x32_bf16 v[84:87], v[166:169], v[202:205], v[84:87]
	v_mfma_f32_16x16x32_bf16 v[80:83], v[178:181], v[202:205], v[80:83]
	v_mfma_f32_16x16x32_bf16 v[68:71], v[166:169], v[210:213], v[68:71]
	v_mfma_f32_16x16x32_bf16 v[64:67], v[178:181], v[210:213], v[64:67]
	v_mfma_f32_16x16x32_bf16 v[116:119], v[174:177], v[190:193], v[116:119]
	v_mfma_f32_16x16x32_bf16 v[112:115], v[182:185], v[190:193], v[112:115]
	v_mfma_f32_16x16x32_bf16 v[100:103], v[174:177], v[198:201], v[100:103]
	v_mfma_f32_16x16x32_bf16 v[96:99], v[182:185], v[198:201], v[96:99]
	v_mfma_f32_16x16x32_bf16 v[84:87], v[174:177], v[206:209], v[84:87]
	v_mfma_f32_16x16x32_bf16 v[80:83], v[182:185], v[206:209], v[80:83]
	v_mfma_f32_16x16x32_bf16 v[68:71], v[174:177], v[214:217], v[68:71]
	v_mfma_f32_16x16x32_bf16 v[64:67], v[182:185], v[214:217], v[64:67]
	s_barrier
	s_setprio 0
	s_add_i32 s24, s50, s28
	v_lshl_add_u64 v[146:147], v[146:147], 0, s[12:13]
	s_mov_b32 m0, s24
	ds_read_b128 v[186:189], v153 offset:49152
	ds_read_b128 v[190:193], v153 offset:50176
	ds_read_b128 v[194:197], v153 offset:51200
	ds_read_b128 v[198:201], v153 offset:52224
	ds_read_b128 v[202:205], v153 offset:53248
	ds_read_b128 v[206:209], v153 offset:54272
	ds_read_b128 v[210:213], v153 offset:55296
	ds_read_b128 v[214:217], v153 offset:56320
	global_load_lds_dwordx4 v[146:147], off
	s_add_i32 m0, s24, 0x2000
	s_add_u32 s22, s22, 0x160080
	v_lshl_add_u64 v[146:147], v[170:171], 0, s[12:13]
	s_addc_u32 s23, s23, 0
	s_add_i32 s24, s51, s28
	global_load_lds_dwordx4 v[146:147], off
	v_lshl_add_u64 v[146:147], s[22:23], 0, v[128:129]
	s_mov_b32 m0, s24
	s_nop 0
	global_load_lds_dwordx4 v[146:147], off
	v_lshl_add_u64 v[146:147], s[22:23], 0, v[130:131]
	s_add_i32 m0, s24, 0x2000
	s_nop 0
	global_load_lds_dwordx4 v[146:147], off
	v_lshl_add_u64 v[146:147], v[218:219], 0, s[12:13]
	s_mov_b32 m0, s35
	s_nop 0
	global_load_lds_dwordx4 v[146:147], off
	v_lshl_add_u64 v[146:147], v[220:221], 0, s[12:13]
	s_mov_b32 m0, s36
	s_nop 0
	global_load_lds_dwordx4 v[146:147], off
	s_waitcnt vmcnt(8)
	s_waitcnt lgkmcnt(0)
	s_setprio 1
	s_barrier
	s_waitcnt lgkmcnt(0)
	v_mfma_f32_16x16x32_bf16 v[60:63], v[142:145], v[186:189], v[60:63]
	v_mfma_f32_16x16x32_bf16 v[56:59], v[158:161], v[186:189], v[56:59]
	v_mfma_f32_16x16x32_bf16 v[44:47], v[142:145], v[194:197], v[44:47]
	v_mfma_f32_16x16x32_bf16 v[40:43], v[158:161], v[194:197], v[40:43]
	v_mfma_f32_16x16x32_bf16 v[28:31], v[142:145], v[202:205], v[28:31]
	v_mfma_f32_16x16x32_bf16 v[24:27], v[158:161], v[202:205], v[24:27]
	v_mfma_f32_16x16x32_bf16 v[12:15], v[142:145], v[210:213], v[12:15]
	v_mfma_f32_16x16x32_bf16 v[8:11], v[158:161], v[210:213], v[8:11]
	v_mfma_f32_16x16x32_bf16 v[60:63], v[154:157], v[190:193], v[60:63]
	v_mfma_f32_16x16x32_bf16 v[56:59], v[162:165], v[190:193], v[56:59]
	v_mfma_f32_16x16x32_bf16 v[44:47], v[154:157], v[198:201], v[44:47]
	v_mfma_f32_16x16x32_bf16 v[40:43], v[162:165], v[198:201], v[40:43]
	v_mfma_f32_16x16x32_bf16 v[28:31], v[154:157], v[206:209], v[28:31]
	v_mfma_f32_16x16x32_bf16 v[24:27], v[162:165], v[206:209], v[24:27]
	v_mfma_f32_16x16x32_bf16 v[12:15], v[154:157], v[214:217], v[12:15]
	v_mfma_f32_16x16x32_bf16 v[8:11], v[162:165], v[214:217], v[8:11]
	s_setprio 0
	s_setprio 1
	v_mfma_f32_16x16x32_bf16 v[52:55], v[166:169], v[186:189], v[52:55]
	v_mfma_f32_16x16x32_bf16 v[48:51], v[178:181], v[186:189], v[48:51]
	v_mfma_f32_16x16x32_bf16 v[36:39], v[166:169], v[194:197], v[36:39]
	v_mfma_f32_16x16x32_bf16 v[32:35], v[178:181], v[194:197], v[32:35]
	v_mfma_f32_16x16x32_bf16 v[20:23], v[166:169], v[202:205], v[20:23]
	v_mfma_f32_16x16x32_bf16 v[16:19], v[178:181], v[202:205], v[16:19]
	v_mfma_f32_16x16x32_bf16 v[4:7], v[166:169], v[210:213], v[4:7]
	v_mfma_f32_16x16x32_bf16 v[0:3], v[178:181], v[210:213], v[0:3]
	v_mfma_f32_16x16x32_bf16 v[52:55], v[174:177], v[190:193], v[52:55]
	v_mfma_f32_16x16x32_bf16 v[48:51], v[182:185], v[190:193], v[48:51]
	v_mfma_f32_16x16x32_bf16 v[36:39], v[174:177], v[198:201], v[36:39]
	v_mfma_f32_16x16x32_bf16 v[32:35], v[182:185], v[198:201], v[32:35]
	v_mfma_f32_16x16x32_bf16 v[20:23], v[174:177], v[206:209], v[20:23]
	v_mfma_f32_16x16x32_bf16 v[16:19], v[182:185], v[206:209], v[16:19]
	v_mfma_f32_16x16x32_bf16 v[4:7], v[174:177], v[214:217], v[4:7]
	v_mfma_f32_16x16x32_bf16 v[0:3], v[182:185], v[214:217], v[0:3]
	s_barrier
	s_setprio 0
	s_add_i32 s49, s49, 2
	s_add_u32 s2, s2, 0x100
	s_addc_u32 s3, s3, 0
	s_add_u32 s47, s47, 0x100
	s_addc_u32 s48, s48, 0
	s_cmpk_gt_u32 s49, 0x55
	s_cbranch_scc0 .LBB0_1294
	s_and_b64 vcc, exec, s[14:15]
	s_cbranch_vccz .LBB0_1297
	s_barrier
